# first K-loop iteration of every unit peeled with zero C operand (no accumulator clearing) in P1 P3 P6; attention row-max trims
# baseline (speedup 1.0000x reference)
.LBB0_174:
	s_ashr_i32 s55, s54, 31
	s_lshl_b64 s[6:7], s[54:55], 19
	s_add_u32 s56, s18, s6
	s_addc_u32 s57, s19, s7
	s_and_b64 s[6:7], s[0:1], exec
	s_cselect_b32 s5, s57, s61
	s_cselect_b32 s8, s56, s60
	s_ashr_i32 s49, s48, 31
	s_lshl_b64 s[6:7], s[48:49], 19
	s_add_u32 s58, s52, s6
	s_addc_u32 s59, s53, s7
	s_and_b64 s[6:7], s[0:1], exec
	s_cselect_b32 s30, s59, s65
	s_cselect_b32 s31, s58, s64
	s_add_u32 s60, s60, 0x40080
	s_addc_u32 s61, s61, 0
	s_add_u32 s49, s64, 0x100
	s_addc_u32 s55, s65, 0
	s_mov_b32 s63, -2
	s_branch .Lrwp1_first
.LBB0_175:
	ds_read_b128 v[148:151], v159
	ds_read_b128 v[152:155], v159 offset:1024
	ds_read_b128 v[164:167], v159 offset:2048
	ds_read_b128 v[168:171], v159 offset:3072
	ds_read_b128 v[172:175], v160
	ds_read_b128 v[176:179], v160 offset:1024
	ds_read_b128 v[180:183], v160 offset:2048
	ds_read_b128 v[184:187], v160 offset:3072
	s_add_u32 s6, s60, 0xfffc0080
	s_addc_u32 s7, s61, -1
	s_cmp_eq_u32 s63, 12
	s_cselect_b32 s67, s5, s7
	s_cselect_b32 s66, s8, s6
	s_cselect_b32 s65, s30, s55
	s_cselect_b32 s64, s31, s49
	v_lshl_add_u64 v[220:221], s[60:61], 0, v[140:141]
	s_add_i32 m0, s72, 0xc000
	ds_read_b128 v[188:191], v161
	ds_read_b128 v[192:195], v161 offset:1024
	ds_read_b128 v[196:199], v161 offset:2048
	ds_read_b128 v[200:203], v161 offset:3072
	ds_read_b128 v[204:207], v161 offset:4096
	ds_read_b128 v[208:211], v161 offset:5120
	ds_read_b128 v[212:215], v161 offset:6144
	ds_read_b128 v[216:219], v161 offset:7168
	global_load_lds_dwordx4 v[220:221], off
	v_lshl_add_u64 v[220:221], s[60:61], 0, v[142:143]
	s_add_i32 m0, s72, 0xe000
	s_nop 0
	global_load_lds_dwordx4 v[220:221], off
	s_waitcnt vmcnt(8)
	s_waitcnt lgkmcnt(0)
	s_barrier
	s_setprio 1
	s_waitcnt lgkmcnt(0)
	v_mfma_f32_16x16x32_bf16 v[126:129], v[148:151], v[188:191], v[126:129]
	v_mfma_f32_16x16x32_bf16 v[122:125], v[164:167], v[188:191], v[122:125]
	v_mfma_f32_16x16x32_bf16 v[110:113], v[148:151], v[196:199], v[110:113]
	v_mfma_f32_16x16x32_bf16 v[106:109], v[164:167], v[196:199], v[106:109]
	v_mfma_f32_16x16x32_bf16 v[94:97], v[148:151], v[204:207], v[94:97]
	v_mfma_f32_16x16x32_bf16 v[90:93], v[164:167], v[204:207], v[90:93]
	v_mfma_f32_16x16x32_bf16 v[78:81], v[148:151], v[212:215], v[78:81]
	v_mfma_f32_16x16x32_bf16 v[74:77], v[164:167], v[212:215], v[74:77]
	v_mfma_f32_16x16x32_bf16 v[126:129], v[152:155], v[192:195], v[126:129]
	v_mfma_f32_16x16x32_bf16 v[122:125], v[168:171], v[192:195], v[122:125]
	v_mfma_f32_16x16x32_bf16 v[110:113], v[152:155], v[200:203], v[110:113]
	v_mfma_f32_16x16x32_bf16 v[106:109], v[168:171], v[200:203], v[106:109]
	v_mfma_f32_16x16x32_bf16 v[94:97], v[152:155], v[208:211], v[94:97]
	v_mfma_f32_16x16x32_bf16 v[90:93], v[168:171], v[208:211], v[90:93]
	v_mfma_f32_16x16x32_bf16 v[78:81], v[152:155], v[216:219], v[78:81]
	v_mfma_f32_16x16x32_bf16 v[74:77], v[168:171], v[216:219], v[74:77]
	s_setprio 0
	s_setprio 1
	v_mfma_f32_16x16x32_bf16 v[118:121], v[172:175], v[188:191], v[118:121]
	v_mfma_f32_16x16x32_bf16 v[114:117], v[180:183], v[188:191], v[114:117]
	v_mfma_f32_16x16x32_bf16 v[102:105], v[172:175], v[196:199], v[102:105]
	v_mfma_f32_16x16x32_bf16 v[98:101], v[180:183], v[196:199], v[98:101]
	v_mfma_f32_16x16x32_bf16 v[86:89], v[172:175], v[204:207], v[86:89]
	v_mfma_f32_16x16x32_bf16 v[82:85], v[180:183], v[204:207], v[82:85]
	v_mfma_f32_16x16x32_bf16 v[70:73], v[172:175], v[212:215], v[70:73]
	v_mfma_f32_16x16x32_bf16 v[66:69], v[180:183], v[212:215], v[66:69]
	v_mfma_f32_16x16x32_bf16 v[118:121], v[176:179], v[192:195], v[118:121]
	v_mfma_f32_16x16x32_bf16 v[114:117], v[184:187], v[192:195], v[114:117]
	v_mfma_f32_16x16x32_bf16 v[102:105], v[176:179], v[200:203], v[102:105]
	v_mfma_f32_16x16x32_bf16 v[98:101], v[184:187], v[200:203], v[98:101]
	v_mfma_f32_16x16x32_bf16 v[86:89], v[176:179], v[208:211], v[86:89]
	v_mfma_f32_16x16x32_bf16 v[82:85], v[184:187], v[208:211], v[82:85]
	v_mfma_f32_16x16x32_bf16 v[70:73], v[176:179], v[216:219], v[70:73]
	v_mfma_f32_16x16x32_bf16 v[66:69], v[184:187], v[216:219], v[66:69]
	s_setprio 0
	s_barrier
	s_add_i32 s6, s85, s47
	v_lshl_add_u64 v[220:221], s[64:65], 0, v[132:133]
	s_mov_b32 m0, s6
	ds_read_b128 v[188:191], v161 offset:16384
	ds_read_b128 v[192:195], v161 offset:17408
	ds_read_b128 v[196:199], v161 offset:18432
	ds_read_b128 v[200:203], v161 offset:19456
	ds_read_b128 v[204:207], v161 offset:20480
	ds_read_b128 v[208:211], v161 offset:21504
	ds_read_b128 v[212:215], v161 offset:22528
	ds_read_b128 v[216:219], v161 offset:23552
	global_load_lds_dwordx4 v[220:221], off
	s_add_i32 m0, s6, 0x2000
	s_add_u32 s6, s64, 0x40000
	v_lshl_add_u64 v[222:223], s[64:65], 0, v[136:137]
	s_addc_u32 s7, s65, 0
	s_add_i32 s88, s86, s47
	global_load_lds_dwordx4 v[222:223], off
	v_lshl_add_u64 v[224:225], s[6:7], 0, v[132:133]
	s_mov_b32 m0, s88
	v_lshl_add_u64 v[226:227], s[66:67], 0, v[134:135]
	global_load_lds_dwordx4 v[224:225], off
	v_lshl_add_u64 v[224:225], s[6:7], 0, v[136:137]
	s_add_i32 m0, s88, 0x2000
	s_nop 0
	global_load_lds_dwordx4 v[224:225], off
	v_lshl_add_u64 v[224:225], s[66:67], 0, v[130:131]
	s_mov_b32 m0, s72
	s_nop 0
	global_load_lds_dwordx4 v[224:225], off
	s_mov_b32 m0, s73
	s_nop 0
	global_load_lds_dwordx4 v[226:227], off
	s_waitcnt vmcnt(8)
	s_waitcnt lgkmcnt(0)
	s_barrier
	s_setprio 1
	s_waitcnt lgkmcnt(0)
	v_mfma_f32_16x16x32_bf16 v[62:65], v[148:151], v[188:191], v[62:65]
	v_mfma_f32_16x16x32_bf16 v[58:61], v[164:167], v[188:191], v[58:61]
	v_mfma_f32_16x16x32_bf16 v[46:49], v[148:151], v[196:199], v[46:49]
	v_mfma_f32_16x16x32_bf16 v[42:45], v[164:167], v[196:199], v[42:45]
	v_mfma_f32_16x16x32_bf16 v[30:33], v[148:151], v[204:207], v[30:33]
	v_mfma_f32_16x16x32_bf16 v[26:29], v[164:167], v[204:207], v[26:29]
	v_mfma_f32_16x16x32_bf16 v[14:17], v[148:151], v[212:215], v[14:17]
	v_mfma_f32_16x16x32_bf16 v[10:13], v[164:167], v[212:215], v[10:13]
	v_mfma_f32_16x16x32_bf16 v[62:65], v[152:155], v[192:195], v[62:65]
	v_mfma_f32_16x16x32_bf16 v[58:61], v[168:171], v[192:195], v[58:61]
	v_mfma_f32_16x16x32_bf16 v[46:49], v[152:155], v[200:203], v[46:49]
	v_mfma_f32_16x16x32_bf16 v[42:45], v[168:171], v[200:203], v[42:45]
	v_mfma_f32_16x16x32_bf16 v[30:33], v[152:155], v[208:211], v[30:33]
	v_mfma_f32_16x16x32_bf16 v[26:29], v[168:171], v[208:211], v[26:29]
	v_mfma_f32_16x16x32_bf16 v[14:17], v[152:155], v[216:219], v[14:17]
	v_mfma_f32_16x16x32_bf16 v[10:13], v[168:171], v[216:219], v[10:13]
	s_setprio 0
	s_setprio 1
	v_mfma_f32_16x16x32_bf16 v[54:57], v[172:175], v[188:191], v[54:57]
	v_mfma_f32_16x16x32_bf16 v[50:53], v[180:183], v[188:191], v[50:53]
	v_mfma_f32_16x16x32_bf16 v[38:41], v[172:175], v[196:199], v[38:41]
	v_mfma_f32_16x16x32_bf16 v[34:37], v[180:183], v[196:199], v[34:37]
	v_mfma_f32_16x16x32_bf16 v[22:25], v[172:175], v[204:207], v[22:25]
	v_mfma_f32_16x16x32_bf16 v[18:21], v[180:183], v[204:207], v[18:21]
	v_mfma_f32_16x16x32_bf16 v[6:9], v[172:175], v[212:215], v[6:9]
	v_mfma_f32_16x16x32_bf16 v[2:5], v[180:183], v[212:215], v[2:5]
	v_mfma_f32_16x16x32_bf16 v[54:57], v[176:179], v[192:195], v[54:57]
	v_mfma_f32_16x16x32_bf16 v[50:53], v[184:187], v[192:195], v[50:53]
	v_mfma_f32_16x16x32_bf16 v[38:41], v[176:179], v[200:203], v[38:41]
	v_mfma_f32_16x16x32_bf16 v[34:37], v[184:187], v[200:203], v[34:37]
	v_mfma_f32_16x16x32_bf16 v[22:25], v[176:179], v[208:211], v[22:25]
	v_mfma_f32_16x16x32_bf16 v[18:21], v[184:187], v[208:211], v[18:21]
	v_mfma_f32_16x16x32_bf16 v[6:9], v[176:179], v[216:219], v[6:9]
	v_mfma_f32_16x16x32_bf16 v[2:5], v[184:187], v[216:219], v[2:5]
	s_setprio 0
	s_barrier
	s_add_i32 s88, 0, 0x18000
	v_add_u32_e32 v138, s88, v158
	s_add_i32 s89, 0, 0x1c000
	ds_read_b128 v[148:151], v138
	ds_read_b128 v[152:155], v138 offset:1024
	ds_read_b128 v[164:167], v138 offset:2048
	ds_read_b128 v[168:171], v138 offset:3072
	v_add_u32_e32 v138, s89, v158
	ds_read_b128 v[172:175], v138
	ds_read_b128 v[176:179], v138 offset:1024
	ds_read_b128 v[180:183], v138 offset:2048
	ds_read_b128 v[184:187], v138 offset:3072
	s_add_u32 s6, s66, 0x40000
	s_addc_u32 s7, s67, 0
	s_mov_b32 m0, s74
	v_lshl_add_u64 v[228:229], s[6:7], 0, v[130:131]
	ds_read_b128 v[188:191], v161 offset:32768
	ds_read_b128 v[192:195], v161 offset:33792
	ds_read_b128 v[196:199], v161 offset:34816
	ds_read_b128 v[200:203], v161 offset:35840
	ds_read_b128 v[204:207], v161 offset:36864
	ds_read_b128 v[208:211], v161 offset:37888
	ds_read_b128 v[212:215], v161 offset:38912
	ds_read_b128 v[216:219], v161 offset:39936
	global_load_lds_dwordx4 v[228:229], off
	v_lshl_add_u64 v[228:229], s[6:7], 0, v[134:135]
	s_mov_b32 m0, s75
	s_nop 0
	global_load_lds_dwordx4 v[228:229], off
	s_waitcnt vmcnt(8)
	s_waitcnt lgkmcnt(0)
	s_barrier
	s_setprio 1
	s_waitcnt lgkmcnt(0)
	v_mfma_f32_16x16x32_bf16 v[126:129], v[148:151], v[188:191], v[126:129]
	v_mfma_f32_16x16x32_bf16 v[122:125], v[164:167], v[188:191], v[122:125]
	v_mfma_f32_16x16x32_bf16 v[110:113], v[148:151], v[196:199], v[110:113]
	v_mfma_f32_16x16x32_bf16 v[106:109], v[164:167], v[196:199], v[106:109]
	v_mfma_f32_16x16x32_bf16 v[94:97], v[148:151], v[204:207], v[94:97]
	v_mfma_f32_16x16x32_bf16 v[90:93], v[164:167], v[204:207], v[90:93]
	v_mfma_f32_16x16x32_bf16 v[78:81], v[148:151], v[212:215], v[78:81]
	v_mfma_f32_16x16x32_bf16 v[74:77], v[164:167], v[212:215], v[74:77]
	v_mfma_f32_16x16x32_bf16 v[126:129], v[152:155], v[192:195], v[126:129]
	v_mfma_f32_16x16x32_bf16 v[122:125], v[168:171], v[192:195], v[122:125]
	v_mfma_f32_16x16x32_bf16 v[110:113], v[152:155], v[200:203], v[110:113]
	v_mfma_f32_16x16x32_bf16 v[106:109], v[168:171], v[200:203], v[106:109]
	v_mfma_f32_16x16x32_bf16 v[94:97], v[152:155], v[208:211], v[94:97]
	v_mfma_f32_16x16x32_bf16 v[90:93], v[168:171], v[208:211], v[90:93]
	v_mfma_f32_16x16x32_bf16 v[78:81], v[152:155], v[216:219], v[78:81]
	v_mfma_f32_16x16x32_bf16 v[74:77], v[168:171], v[216:219], v[74:77]
	s_setprio 0
	s_setprio 1
	v_mfma_f32_16x16x32_bf16 v[118:121], v[172:175], v[188:191], v[118:121]
	v_mfma_f32_16x16x32_bf16 v[114:117], v[180:183], v[188:191], v[114:117]
	v_mfma_f32_16x16x32_bf16 v[102:105], v[172:175], v[196:199], v[102:105]
	v_mfma_f32_16x16x32_bf16 v[98:101], v[180:183], v[196:199], v[98:101]
	v_mfma_f32_16x16x32_bf16 v[86:89], v[172:175], v[204:207], v[86:89]
	v_mfma_f32_16x16x32_bf16 v[82:85], v[180:183], v[204:207], v[82:85]
	v_mfma_f32_16x16x32_bf16 v[70:73], v[172:175], v[212:215], v[70:73]
	v_mfma_f32_16x16x32_bf16 v[66:69], v[180:183], v[212:215], v[66:69]
	v_mfma_f32_16x16x32_bf16 v[118:121], v[176:179], v[192:195], v[118:121]
	v_mfma_f32_16x16x32_bf16 v[114:117], v[184:187], v[192:195], v[114:117]
	v_mfma_f32_16x16x32_bf16 v[102:105], v[176:179], v[200:203], v[102:105]
	v_mfma_f32_16x16x32_bf16 v[98:101], v[184:187], v[200:203], v[98:101]
	v_mfma_f32_16x16x32_bf16 v[86:89], v[176:179], v[208:211], v[86:89]
	v_mfma_f32_16x16x32_bf16 v[82:85], v[184:187], v[208:211], v[82:85]
	v_mfma_f32_16x16x32_bf16 v[70:73], v[176:179], v[216:219], v[70:73]
	v_mfma_f32_16x16x32_bf16 v[66:69], v[184:187], v[216:219], v[66:69]
	s_setprio 0
	s_barrier
	s_add_i32 s6, s88, s47
	v_lshl_add_u64 v[220:221], v[220:221], 0, s[20:21]
	s_mov_b32 m0, s6
	ds_read_b128 v[188:191], v161 offset:49152
	ds_read_b128 v[192:195], v161 offset:50176
	ds_read_b128 v[196:199], v161 offset:51200
	ds_read_b128 v[200:203], v161 offset:52224
	ds_read_b128 v[204:207], v161 offset:53248
	ds_read_b128 v[208:211], v161 offset:54272
	ds_read_b128 v[212:215], v161 offset:55296
	ds_read_b128 v[216:219], v161 offset:56320
	global_load_lds_dwordx4 v[220:221], off
	s_add_i32 m0, s6, 0x2000
	s_add_u32 s6, s64, 0x40080
	v_lshl_add_u64 v[220:221], v[222:223], 0, s[20:21]
	s_addc_u32 s7, s65, 0
	s_add_i32 s64, s89, s47
	global_load_lds_dwordx4 v[220:221], off
	v_lshl_add_u64 v[220:221], s[6:7], 0, v[132:133]
	s_mov_b32 m0, s64
	s_nop 0
	global_load_lds_dwordx4 v[220:221], off
	v_lshl_add_u64 v[220:221], s[6:7], 0, v[136:137]
	s_add_i32 m0, s64, 0x2000
	s_nop 0
	global_load_lds_dwordx4 v[220:221], off
	v_lshl_add_u64 v[220:221], v[224:225], 0, s[20:21]
	s_mov_b32 m0, s77
	s_nop 0
	global_load_lds_dwordx4 v[220:221], off
	v_lshl_add_u64 v[220:221], v[226:227], 0, s[20:21]
	s_mov_b32 m0, s78
	s_nop 0
	global_load_lds_dwordx4 v[220:221], off
	s_waitcnt vmcnt(8)
	s_waitcnt lgkmcnt(0)
	s_barrier
	s_setprio 1
	s_waitcnt lgkmcnt(0)
	v_mfma_f32_16x16x32_bf16 v[62:65], v[148:151], v[188:191], v[62:65]
	v_mfma_f32_16x16x32_bf16 v[58:61], v[164:167], v[188:191], v[58:61]
	v_mfma_f32_16x16x32_bf16 v[46:49], v[148:151], v[196:199], v[46:49]
	v_mfma_f32_16x16x32_bf16 v[42:45], v[164:167], v[196:199], v[42:45]
	v_mfma_f32_16x16x32_bf16 v[30:33], v[148:151], v[204:207], v[30:33]
	v_mfma_f32_16x16x32_bf16 v[26:29], v[164:167], v[204:207], v[26:29]
	v_mfma_f32_16x16x32_bf16 v[14:17], v[148:151], v[212:215], v[14:17]
	v_mfma_f32_16x16x32_bf16 v[10:13], v[164:167], v[212:215], v[10:13]
	v_mfma_f32_16x16x32_bf16 v[62:65], v[152:155], v[192:195], v[62:65]
	v_mfma_f32_16x16x32_bf16 v[58:61], v[168:171], v[192:195], v[58:61]
	v_mfma_f32_16x16x32_bf16 v[46:49], v[152:155], v[200:203], v[46:49]
	v_mfma_f32_16x16x32_bf16 v[42:45], v[168:171], v[200:203], v[42:45]
	v_mfma_f32_16x16x32_bf16 v[30:33], v[152:155], v[208:211], v[30:33]
	v_mfma_f32_16x16x32_bf16 v[26:29], v[168:171], v[208:211], v[26:29]
	v_mfma_f32_16x16x32_bf16 v[14:17], v[152:155], v[216:219], v[14:17]
	v_mfma_f32_16x16x32_bf16 v[10:13], v[168:171], v[216:219], v[10:13]
	s_setprio 0
	s_setprio 1
	v_mfma_f32_16x16x32_bf16 v[54:57], v[172:175], v[188:191], v[54:57]
	v_mfma_f32_16x16x32_bf16 v[50:53], v[180:183], v[188:191], v[50:53]
	v_mfma_f32_16x16x32_bf16 v[38:41], v[172:175], v[196:199], v[38:41]
	v_mfma_f32_16x16x32_bf16 v[34:37], v[180:183], v[196:199], v[34:37]
	v_mfma_f32_16x16x32_bf16 v[22:25], v[172:175], v[204:207], v[22:25]
	v_mfma_f32_16x16x32_bf16 v[18:21], v[180:183], v[204:207], v[18:21]
	v_mfma_f32_16x16x32_bf16 v[6:9], v[172:175], v[212:215], v[6:9]
	v_mfma_f32_16x16x32_bf16 v[2:5], v[180:183], v[212:215], v[2:5]
	v_mfma_f32_16x16x32_bf16 v[54:57], v[176:179], v[192:195], v[54:57]
	v_mfma_f32_16x16x32_bf16 v[50:53], v[184:187], v[192:195], v[50:53]
	v_mfma_f32_16x16x32_bf16 v[38:41], v[176:179], v[200:203], v[38:41]
	v_mfma_f32_16x16x32_bf16 v[34:37], v[184:187], v[200:203], v[34:37]
	v_mfma_f32_16x16x32_bf16 v[22:25], v[176:179], v[208:211], v[22:25]
	v_mfma_f32_16x16x32_bf16 v[18:21], v[184:187], v[208:211], v[18:21]
	v_mfma_f32_16x16x32_bf16 v[6:9], v[176:179], v[216:219], v[6:9]
	v_mfma_f32_16x16x32_bf16 v[2:5], v[184:187], v[216:219], v[2:5]
	s_setprio 0
	s_barrier
	s_add_i32 s63, s63, 2
	s_add_u32 s60, s60, 0x100
	s_addc_u32 s61, s61, 0
	s_add_u32 s49, s49, 0x100
	s_addc_u32 s55, s55, 0
	s_cmp_gt_u32 s63, 13
	s_cbranch_scc0 .LBB0_175
.Lrwp1_exit:
	s_and_b64 vcc, exec, s[44:45]
	s_cbranch_vccz .LBB0_178
	s_barrier

.Lrwp1_first:
	ds_read_b128 v[148:151], v159
	ds_read_b128 v[152:155], v159 offset:1024
	ds_read_b128 v[164:167], v159 offset:2048
	ds_read_b128 v[168:171], v159 offset:3072
	ds_read_b128 v[172:175], v160
	ds_read_b128 v[176:179], v160 offset:1024
	ds_read_b128 v[180:183], v160 offset:2048
	ds_read_b128 v[184:187], v160 offset:3072
	s_add_u32 s6, s60, 0xfffc0080
	s_addc_u32 s7, s61, -1
	s_cmp_eq_u32 s63, 12
	s_cselect_b32 s67, s5, s7
	s_cselect_b32 s66, s8, s6
	s_cselect_b32 s65, s30, s55
	s_cselect_b32 s64, s31, s49
	v_lshl_add_u64 v[220:221], s[60:61], 0, v[140:141]
	s_add_i32 m0, s72, 0xc000
	ds_read_b128 v[188:191], v161
	ds_read_b128 v[192:195], v161 offset:1024
	ds_read_b128 v[196:199], v161 offset:2048
	ds_read_b128 v[200:203], v161 offset:3072
	ds_read_b128 v[204:207], v161 offset:4096
	ds_read_b128 v[208:211], v161 offset:5120
	ds_read_b128 v[212:215], v161 offset:6144
	ds_read_b128 v[216:219], v161 offset:7168
	global_load_lds_dwordx4 v[220:221], off
	v_lshl_add_u64 v[220:221], s[60:61], 0, v[142:143]
	s_add_i32 m0, s72, 0xe000
	s_nop 0
	global_load_lds_dwordx4 v[220:221], off
	s_cmp_eq_u32 s98, 0xffff0000
	s_cbranch_scc1 .Lrwp1_a16
	s_cmp_eq_u32 s98, -1
	s_cbranch_scc1 .Lrwp1_a32
	s_waitcnt vmcnt(8)
	s_branch .Lrwp1_adone

.Lrwp1_adone:
	s_waitcnt lgkmcnt(0)
	s_barrier
	s_setprio 1
	s_waitcnt lgkmcnt(0)
	v_mfma_f32_16x16x32_bf16 v[126:129], v[148:151], v[188:191], 0
	v_mfma_f32_16x16x32_bf16 v[122:125], v[164:167], v[188:191], 0
	v_mfma_f32_16x16x32_bf16 v[110:113], v[148:151], v[196:199], 0
	v_mfma_f32_16x16x32_bf16 v[106:109], v[164:167], v[196:199], 0
	v_mfma_f32_16x16x32_bf16 v[94:97], v[148:151], v[204:207], 0
	v_mfma_f32_16x16x32_bf16 v[90:93], v[164:167], v[204:207], 0
	v_mfma_f32_16x16x32_bf16 v[78:81], v[148:151], v[212:215], 0
	v_mfma_f32_16x16x32_bf16 v[74:77], v[164:167], v[212:215], 0
	v_mfma_f32_16x16x32_bf16 v[126:129], v[152:155], v[192:195], v[126:129]
	v_mfma_f32_16x16x32_bf16 v[122:125], v[168:171], v[192:195], v[122:125]
	v_mfma_f32_16x16x32_bf16 v[110:113], v[152:155], v[200:203], v[110:113]
	v_mfma_f32_16x16x32_bf16 v[106:109], v[168:171], v[200:203], v[106:109]
	v_mfma_f32_16x16x32_bf16 v[94:97], v[152:155], v[208:211], v[94:97]
	v_mfma_f32_16x16x32_bf16 v[90:93], v[168:171], v[208:211], v[90:93]
	v_mfma_f32_16x16x32_bf16 v[78:81], v[152:155], v[216:219], v[78:81]
	v_mfma_f32_16x16x32_bf16 v[74:77], v[168:171], v[216:219], v[74:77]
	s_setprio 0
	s_setprio 1
	v_mfma_f32_16x16x32_bf16 v[118:121], v[172:175], v[188:191], 0
	v_mfma_f32_16x16x32_bf16 v[114:117], v[180:183], v[188:191], 0
	v_mfma_f32_16x16x32_bf16 v[102:105], v[172:175], v[196:199], 0
	v_mfma_f32_16x16x32_bf16 v[98:101], v[180:183], v[196:199], 0
	v_mfma_f32_16x16x32_bf16 v[86:89], v[172:175], v[204:207], 0
	v_mfma_f32_16x16x32_bf16 v[82:85], v[180:183], v[204:207], 0
	v_mfma_f32_16x16x32_bf16 v[70:73], v[172:175], v[212:215], 0
	v_mfma_f32_16x16x32_bf16 v[66:69], v[180:183], v[212:215], 0
	v_mfma_f32_16x16x32_bf16 v[118:121], v[176:179], v[192:195], v[118:121]
	v_mfma_f32_16x16x32_bf16 v[114:117], v[184:187], v[192:195], v[114:117]
	v_mfma_f32_16x16x32_bf16 v[102:105], v[176:179], v[200:203], v[102:105]
	v_mfma_f32_16x16x32_bf16 v[98:101], v[184:187], v[200:203], v[98:101]
	v_mfma_f32_16x16x32_bf16 v[86:89], v[176:179], v[208:211], v[86:89]
	v_mfma_f32_16x16x32_bf16 v[82:85], v[184:187], v[208:211], v[82:85]
	v_mfma_f32_16x16x32_bf16 v[70:73], v[176:179], v[216:219], v[70:73]
	v_mfma_f32_16x16x32_bf16 v[66:69], v[184:187], v[216:219], v[66:69]
	s_setprio 0
	s_barrier
	s_add_i32 s6, s85, s47
	v_lshl_add_u64 v[220:221], s[64:65], 0, v[132:133]
	s_mov_b32 m0, s6
	ds_read_b128 v[188:191], v161 offset:16384
	ds_read_b128 v[192:195], v161 offset:17408
	ds_read_b128 v[196:199], v161 offset:18432
	ds_read_b128 v[200:203], v161 offset:19456
	ds_read_b128 v[204:207], v161 offset:20480
	ds_read_b128 v[208:211], v161 offset:21504
	ds_read_b128 v[212:215], v161 offset:22528
	ds_read_b128 v[216:219], v161 offset:23552
	global_load_lds_dwordx4 v[220:221], off
	s_add_i32 m0, s6, 0x2000
	s_add_u32 s6, s64, 0x40000
	v_lshl_add_u64 v[222:223], s[64:65], 0, v[136:137]
	s_addc_u32 s7, s65, 0
	s_add_i32 s88, s86, s47
	global_load_lds_dwordx4 v[222:223], off
	v_lshl_add_u64 v[224:225], s[6:7], 0, v[132:133]
	s_mov_b32 m0, s88
	v_lshl_add_u64 v[226:227], s[66:67], 0, v[134:135]
	global_load_lds_dwordx4 v[224:225], off
	v_lshl_add_u64 v[224:225], s[6:7], 0, v[136:137]
	s_add_i32 m0, s88, 0x2000
	s_nop 0
	global_load_lds_dwordx4 v[224:225], off
	v_lshl_add_u64 v[224:225], s[66:67], 0, v[130:131]
	s_mov_b32 m0, s72
	s_nop 0
	global_load_lds_dwordx4 v[224:225], off
	s_mov_b32 m0, s73
	s_nop 0
	global_load_lds_dwordx4 v[226:227], off
	s_cmp_eq_u32 s98, 0xffff0000
	s_cbranch_scc1 .Lrwp1_b16
	s_cmp_eq_u32 s98, -1
	s_cbranch_scc1 .Lrwp1_b32
	s_waitcnt vmcnt(8)
	s_branch .Lrwp1_bdone

.Lrwp1_bdone:
	s_mov_b32 s98, 0
	s_waitcnt lgkmcnt(0)
	s_barrier
	s_setprio 1
	s_waitcnt lgkmcnt(0)
	v_mfma_f32_16x16x32_bf16 v[62:65], v[148:151], v[188:191], 0
	v_mfma_f32_16x16x32_bf16 v[58:61], v[164:167], v[188:191], 0
	v_mfma_f32_16x16x32_bf16 v[46:49], v[148:151], v[196:199], 0
	v_mfma_f32_16x16x32_bf16 v[42:45], v[164:167], v[196:199], 0
	v_mfma_f32_16x16x32_bf16 v[30:33], v[148:151], v[204:207], 0
	v_mfma_f32_16x16x32_bf16 v[26:29], v[164:167], v[204:207], 0
	v_mfma_f32_16x16x32_bf16 v[14:17], v[148:151], v[212:215], 0
	v_mfma_f32_16x16x32_bf16 v[10:13], v[164:167], v[212:215], 0
	v_mfma_f32_16x16x32_bf16 v[62:65], v[152:155], v[192:195], v[62:65]
	v_mfma_f32_16x16x32_bf16 v[58:61], v[168:171], v[192:195], v[58:61]
	v_mfma_f32_16x16x32_bf16 v[46:49], v[152:155], v[200:203], v[46:49]
	v_mfma_f32_16x16x32_bf16 v[42:45], v[168:171], v[200:203], v[42:45]
	v_mfma_f32_16x16x32_bf16 v[30:33], v[152:155], v[208:211], v[30:33]
	v_mfma_f32_16x16x32_bf16 v[26:29], v[168:171], v[208:211], v[26:29]
	v_mfma_f32_16x16x32_bf16 v[14:17], v[152:155], v[216:219], v[14:17]
	v_mfma_f32_16x16x32_bf16 v[10:13], v[168:171], v[216:219], v[10:13]
	s_setprio 0
	s_setprio 1
	v_mfma_f32_16x16x32_bf16 v[54:57], v[172:175], v[188:191], 0
	v_mfma_f32_16x16x32_bf16 v[50:53], v[180:183], v[188:191], 0
	v_mfma_f32_16x16x32_bf16 v[38:41], v[172:175], v[196:199], 0
	v_mfma_f32_16x16x32_bf16 v[34:37], v[180:183], v[196:199], 0
	v_mfma_f32_16x16x32_bf16 v[22:25], v[172:175], v[204:207], 0
	v_mfma_f32_16x16x32_bf16 v[18:21], v[180:183], v[204:207], 0
	v_mfma_f32_16x16x32_bf16 v[6:9], v[172:175], v[212:215], 0
	v_mfma_f32_16x16x32_bf16 v[2:5], v[180:183], v[212:215], 0
	v_mfma_f32_16x16x32_bf16 v[54:57], v[176:179], v[192:195], v[54:57]
	v_mfma_f32_16x16x32_bf16 v[50:53], v[184:187], v[192:195], v[50:53]
	v_mfma_f32_16x16x32_bf16 v[38:41], v[176:179], v[200:203], v[38:41]
	v_mfma_f32_16x16x32_bf16 v[34:37], v[184:187], v[200:203], v[34:37]
	v_mfma_f32_16x16x32_bf16 v[22:25], v[176:179], v[208:211], v[22:25]
	v_mfma_f32_16x16x32_bf16 v[18:21], v[184:187], v[208:211], v[18:21]
	v_mfma_f32_16x16x32_bf16 v[6:9], v[176:179], v[216:219], v[6:9]
	v_mfma_f32_16x16x32_bf16 v[2:5], v[184:187], v[216:219], v[2:5]
	s_setprio 0
	s_barrier
	s_add_i32 s88, 0, 0x18000
	v_add_u32_e32 v138, s88, v158
	s_add_i32 s89, 0, 0x1c000
	ds_read_b128 v[148:151], v138
	ds_read_b128 v[152:155], v138 offset:1024
	ds_read_b128 v[164:167], v138 offset:2048
	ds_read_b128 v[168:171], v138 offset:3072
	v_add_u32_e32 v138, s89, v158
	ds_read_b128 v[172:175], v138
	ds_read_b128 v[176:179], v138 offset:1024
	ds_read_b128 v[180:183], v138 offset:2048
	ds_read_b128 v[184:187], v138 offset:3072
	s_add_u32 s6, s66, 0x40000
	s_addc_u32 s7, s67, 0
	s_mov_b32 m0, s74
	v_lshl_add_u64 v[228:229], s[6:7], 0, v[130:131]
	ds_read_b128 v[188:191], v161 offset:32768
	ds_read_b128 v[192:195], v161 offset:33792
	ds_read_b128 v[196:199], v161 offset:34816
	ds_read_b128 v[200:203], v161 offset:35840
	ds_read_b128 v[204:207], v161 offset:36864
	ds_read_b128 v[208:211], v161 offset:37888
	ds_read_b128 v[212:215], v161 offset:38912
	ds_read_b128 v[216:219], v161 offset:39936
	global_load_lds_dwordx4 v[228:229], off
	v_lshl_add_u64 v[228:229], s[6:7], 0, v[134:135]
	s_mov_b32 m0, s75
	s_nop 0
	global_load_lds_dwordx4 v[228:229], off
	s_waitcnt vmcnt(8)
	s_waitcnt lgkmcnt(0)
	s_barrier
	s_setprio 1
	s_waitcnt lgkmcnt(0)
	v_mfma_f32_16x16x32_bf16 v[126:129], v[148:151], v[188:191], v[126:129]
	v_mfma_f32_16x16x32_bf16 v[122:125], v[164:167], v[188:191], v[122:125]
	v_mfma_f32_16x16x32_bf16 v[110:113], v[148:151], v[196:199], v[110:113]
	v_mfma_f32_16x16x32_bf16 v[106:109], v[164:167], v[196:199], v[106:109]
	v_mfma_f32_16x16x32_bf16 v[94:97], v[148:151], v[204:207], v[94:97]
	v_mfma_f32_16x16x32_bf16 v[90:93], v[164:167], v[204:207], v[90:93]
	v_mfma_f32_16x16x32_bf16 v[78:81], v[148:151], v[212:215], v[78:81]
	v_mfma_f32_16x16x32_bf16 v[74:77], v[164:167], v[212:215], v[74:77]
	v_mfma_f32_16x16x32_bf16 v[126:129], v[152:155], v[192:195], v[126:129]
	v_mfma_f32_16x16x32_bf16 v[122:125], v[168:171], v[192:195], v[122:125]
	v_mfma_f32_16x16x32_bf16 v[110:113], v[152:155], v[200:203], v[110:113]
	v_mfma_f32_16x16x32_bf16 v[106:109], v[168:171], v[200:203], v[106:109]
	v_mfma_f32_16x16x32_bf16 v[94:97], v[152:155], v[208:211], v[94:97]
	v_mfma_f32_16x16x32_bf16 v[90:93], v[168:171], v[208:211], v[90:93]
	v_mfma_f32_16x16x32_bf16 v[78:81], v[152:155], v[216:219], v[78:81]
	v_mfma_f32_16x16x32_bf16 v[74:77], v[168:171], v[216:219], v[74:77]
	s_setprio 0
	s_setprio 1
	v_mfma_f32_16x16x32_bf16 v[118:121], v[172:175], v[188:191], v[118:121]
	v_mfma_f32_16x16x32_bf16 v[114:117], v[180:183], v[188:191], v[114:117]
	v_mfma_f32_16x16x32_bf16 v[102:105], v[172:175], v[196:199], v[102:105]
	v_mfma_f32_16x16x32_bf16 v[98:101], v[180:183], v[196:199], v[98:101]
	v_mfma_f32_16x16x32_bf16 v[86:89], v[172:175], v[204:207], v[86:89]
	v_mfma_f32_16x16x32_bf16 v[82:85], v[180:183], v[204:207], v[82:85]
	v_mfma_f32_16x16x32_bf16 v[70:73], v[172:175], v[212:215], v[70:73]
	v_mfma_f32_16x16x32_bf16 v[66:69], v[180:183], v[212:215], v[66:69]
	v_mfma_f32_16x16x32_bf16 v[118:121], v[176:179], v[192:195], v[118:121]
	v_mfma_f32_16x16x32_bf16 v[114:117], v[184:187], v[192:195], v[114:117]
	v_mfma_f32_16x16x32_bf16 v[102:105], v[176:179], v[200:203], v[102:105]
	v_mfma_f32_16x16x32_bf16 v[98:101], v[184:187], v[200:203], v[98:101]
	v_mfma_f32_16x16x32_bf16 v[86:89], v[176:179], v[208:211], v[86:89]
	v_mfma_f32_16x16x32_bf16 v[82:85], v[184:187], v[208:211], v[82:85]
	v_mfma_f32_16x16x32_bf16 v[70:73], v[176:179], v[216:219], v[70:73]
	v_mfma_f32_16x16x32_bf16 v[66:69], v[184:187], v[216:219], v[66:69]
	s_setprio 0
	s_barrier
	s_add_i32 s6, s88, s47
	v_lshl_add_u64 v[220:221], v[220:221], 0, s[20:21]
	s_mov_b32 m0, s6
	ds_read_b128 v[188:191], v161 offset:49152
	ds_read_b128 v[192:195], v161 offset:50176
	ds_read_b128 v[196:199], v161 offset:51200
	ds_read_b128 v[200:203], v161 offset:52224
	ds_read_b128 v[204:207], v161 offset:53248
	ds_read_b128 v[208:211], v161 offset:54272
	ds_read_b128 v[212:215], v161 offset:55296
	ds_read_b128 v[216:219], v161 offset:56320
	global_load_lds_dwordx4 v[220:221], off
	s_add_i32 m0, s6, 0x2000
	s_add_u32 s6, s64, 0x40080
	v_lshl_add_u64 v[220:221], v[222:223], 0, s[20:21]
	s_addc_u32 s7, s65, 0
	s_add_i32 s64, s89, s47
	global_load_lds_dwordx4 v[220:221], off
	v_lshl_add_u64 v[220:221], s[6:7], 0, v[132:133]
	s_mov_b32 m0, s64
	s_nop 0
	global_load_lds_dwordx4 v[220:221], off
	v_lshl_add_u64 v[220:221], s[6:7], 0, v[136:137]
	s_add_i32 m0, s64, 0x2000
	s_nop 0
	global_load_lds_dwordx4 v[220:221], off
	v_lshl_add_u64 v[220:221], v[224:225], 0, s[20:21]
	s_mov_b32 m0, s77
	s_nop 0
	global_load_lds_dwordx4 v[220:221], off
	v_lshl_add_u64 v[220:221], v[226:227], 0, s[20:21]
	s_mov_b32 m0, s78
	s_nop 0
	global_load_lds_dwordx4 v[220:221], off
	s_waitcnt vmcnt(8)
	s_waitcnt lgkmcnt(0)
	s_barrier
	s_setprio 1
	s_waitcnt lgkmcnt(0)
	v_mfma_f32_16x16x32_bf16 v[62:65], v[148:151], v[188:191], v[62:65]
	v_mfma_f32_16x16x32_bf16 v[58:61], v[164:167], v[188:191], v[58:61]
	v_mfma_f32_16x16x32_bf16 v[46:49], v[148:151], v[196:199], v[46:49]
	v_mfma_f32_16x16x32_bf16 v[42:45], v[164:167], v[196:199], v[42:45]
	v_mfma_f32_16x16x32_bf16 v[30:33], v[148:151], v[204:207], v[30:33]
	v_mfma_f32_16x16x32_bf16 v[26:29], v[164:167], v[204:207], v[26:29]
	v_mfma_f32_16x16x32_bf16 v[14:17], v[148:151], v[212:215], v[14:17]
	v_mfma_f32_16x16x32_bf16 v[10:13], v[164:167], v[212:215], v[10:13]
	v_mfma_f32_16x16x32_bf16 v[62:65], v[152:155], v[192:195], v[62:65]
	v_mfma_f32_16x16x32_bf16 v[58:61], v[168:171], v[192:195], v[58:61]
	v_mfma_f32_16x16x32_bf16 v[46:49], v[152:155], v[200:203], v[46:49]
	v_mfma_f32_16x16x32_bf16 v[42:45], v[168:171], v[200:203], v[42:45]
	v_mfma_f32_16x16x32_bf16 v[30:33], v[152:155], v[208:211], v[30:33]
	v_mfma_f32_16x16x32_bf16 v[26:29], v[168:171], v[208:211], v[26:29]
	v_mfma_f32_16x16x32_bf16 v[14:17], v[152:155], v[216:219], v[14:17]
	v_mfma_f32_16x16x32_bf16 v[10:13], v[168:171], v[216:219], v[10:13]
	s_setprio 0
	s_setprio 1
	v_mfma_f32_16x16x32_bf16 v[54:57], v[172:175], v[188:191], v[54:57]
	v_mfma_f32_16x16x32_bf16 v[50:53], v[180:183], v[188:191], v[50:53]
	v_mfma_f32_16x16x32_bf16 v[38:41], v[172:175], v[196:199], v[38:41]
	v_mfma_f32_16x16x32_bf16 v[34:37], v[180:183], v[196:199], v[34:37]
	v_mfma_f32_16x16x32_bf16 v[22:25], v[172:175], v[204:207], v[22:25]
	v_mfma_f32_16x16x32_bf16 v[18:21], v[180:183], v[204:207], v[18:21]
	v_mfma_f32_16x16x32_bf16 v[6:9], v[172:175], v[212:215], v[6:9]
	v_mfma_f32_16x16x32_bf16 v[2:5], v[180:183], v[212:215], v[2:5]
	v_mfma_f32_16x16x32_bf16 v[54:57], v[176:179], v[192:195], v[54:57]
	v_mfma_f32_16x16x32_bf16 v[50:53], v[184:187], v[192:195], v[50:53]
	v_mfma_f32_16x16x32_bf16 v[38:41], v[176:179], v[200:203], v[38:41]
	v_mfma_f32_16x16x32_bf16 v[34:37], v[184:187], v[200:203], v[34:37]
	v_mfma_f32_16x16x32_bf16 v[22:25], v[176:179], v[208:211], v[22:25]
	v_mfma_f32_16x16x32_bf16 v[18:21], v[184:187], v[208:211], v[18:21]
	v_mfma_f32_16x16x32_bf16 v[6:9], v[176:179], v[216:219], v[6:9]
	v_mfma_f32_16x16x32_bf16 v[2:5], v[184:187], v[216:219], v[2:5]
	s_setprio 0
	s_barrier
	s_add_i32 s63, s63, 2
	s_add_u32 s60, s60, 0x100
	s_addc_u32 s61, s61, 0
	s_add_u32 s49, s49, 0x100
	s_addc_u32 s55, s55, 0
	s_cmp_gt_u32 s63, 13
	s_cbranch_scc0 .LBB0_175
	s_branch .Lrwp1_exit

.LBB0_476:
	v_max3_f32 v78, v50, v51, v34
	v_max3_f32 v124, v52, v53, v35
	v_max3_f32 v78, v78, v36, v37
	v_max3_f32 v124, v124, v56, v57
	v_max3_f32 v78, v78, v54, v55
	v_max3_f32 v124, v124, v40, v41
	v_max3_f32 v78, v78, v38, v39
	v_max3_f32 v124, v124, v60, v61
	v_max3_f32 v78, v78, v58, v59
	v_max3_f32 v124, v124, v44, v45
	v_max3_f32 v78, v78, v42, v43
	v_max3_f32 v124, v124, v64, v65
	v_max3_f32 v78, v78, v62, v63
	v_max3_f32 v124, v124, v48, v49
	v_max3_f32 v78, v78, v46, v47
	v_max_f32_e32 v78, v78, v124
	v_mov_b32_e32 v124, v78
	s_nop 1
	v_permlane32_swap_b32_e32 v78, v124
	v_max_f32_e32 v78, v78, v124
	v_cmp_lt_f32_e32 vcc, s72, v78
	s_nop 1
	v_cndmask_b32_e32 v78, 0, v78, vcc
	v_cmp_neq_f32_e32 vcc, 0, v78
	s_cbranch_vccz .LBB0_464
	v_exp_f32_e64 v124, -v78
	v_pk_add_f32 v[50:51], v[50:51], v[78:79] op_sel_hi:[1,0] neg_lo:[0,1] neg_hi:[0,1]
	v_pk_add_f32 v[34:35], v[34:35], v[78:79] op_sel_hi:[1,0] neg_lo:[0,1] neg_hi:[0,1]
	v_pk_add_f32 v[52:53], v[52:53], v[78:79] op_sel_hi:[1,0] neg_lo:[0,1] neg_hi:[0,1]
	v_pk_add_f32 v[36:37], v[36:37], v[78:79] op_sel_hi:[1,0] neg_lo:[0,1] neg_hi:[0,1]
	v_pk_add_f32 v[54:55], v[54:55], v[78:79] op_sel_hi:[1,0] neg_lo:[0,1] neg_hi:[0,1]
	v_pk_add_f32 v[38:39], v[38:39], v[78:79] op_sel_hi:[1,0] neg_lo:[0,1] neg_hi:[0,1]
	v_pk_add_f32 v[56:57], v[56:57], v[78:79] op_sel_hi:[1,0] neg_lo:[0,1] neg_hi:[0,1]
	v_pk_add_f32 v[40:41], v[40:41], v[78:79] op_sel_hi:[1,0] neg_lo:[0,1] neg_hi:[0,1]
	v_pk_add_f32 v[58:59], v[58:59], v[78:79] op_sel_hi:[1,0] neg_lo:[0,1] neg_hi:[0,1]
	v_pk_add_f32 v[42:43], v[42:43], v[78:79] op_sel_hi:[1,0] neg_lo:[0,1] neg_hi:[0,1]
	v_pk_add_f32 v[60:61], v[60:61], v[78:79] op_sel_hi:[1,0] neg_lo:[0,1] neg_hi:[0,1]
	v_pk_add_f32 v[44:45], v[44:45], v[78:79] op_sel_hi:[1,0] neg_lo:[0,1] neg_hi:[0,1]
	v_pk_add_f32 v[62:63], v[62:63], v[78:79] op_sel_hi:[1,0] neg_lo:[0,1] neg_hi:[0,1]
	v_pk_add_f32 v[46:47], v[46:47], v[78:79] op_sel_hi:[1,0] neg_lo:[0,1] neg_hi:[0,1]
	v_pk_add_f32 v[64:65], v[64:65], v[78:79] op_sel_hi:[1,0] neg_lo:[0,1] neg_hi:[0,1]
	v_pk_add_f32 v[48:49], v[48:49], v[78:79] op_sel_hi:[1,0] neg_lo:[0,1] neg_hi:[0,1]
	v_pk_mul_f32 v[16:17], v[16:17], v[124:125] op_sel_hi:[1,0]
	v_pk_mul_f32 v[14:15], v[14:15], v[124:125] op_sel_hi:[1,0]
	v_pk_mul_f32 v[12:13], v[12:13], v[124:125] op_sel_hi:[1,0]
	v_pk_mul_f32 v[10:11], v[10:11], v[124:125] op_sel_hi:[1,0]
	v_pk_mul_f32 v[8:9], v[8:9], v[124:125] op_sel_hi:[1,0]
	v_pk_mul_f32 v[6:7], v[6:7], v[124:125] op_sel_hi:[1,0]
	v_pk_mul_f32 v[4:5], v[4:5], v[124:125] op_sel_hi:[1,0]
	v_pk_mul_f32 v[2:3], v[2:3], v[124:125] op_sel_hi:[1,0]
	v_pk_mul_f32 v[32:33], v[32:33], v[124:125] op_sel_hi:[1,0]
	v_pk_mul_f32 v[30:31], v[30:31], v[124:125] op_sel_hi:[1,0]
	v_pk_mul_f32 v[28:29], v[28:29], v[124:125] op_sel_hi:[1,0]
	v_pk_mul_f32 v[26:27], v[26:27], v[124:125] op_sel_hi:[1,0]
	v_pk_mul_f32 v[24:25], v[24:25], v[124:125] op_sel_hi:[1,0]
	v_pk_mul_f32 v[22:23], v[22:23], v[124:125] op_sel_hi:[1,0]
	v_pk_mul_f32 v[20:21], v[20:21], v[124:125] op_sel_hi:[1,0]
	v_pk_mul_f32 v[18:19], v[18:19], v[124:125] op_sel_hi:[1,0]
	v_add_f32_e32 v153, v153, v78
	v_mul_f32_e32 v79, v79, v124
	s_branch .LBB0_464

.LBB0_559:
	s_ashr_i32 s59, s58, 31
	s_lshl_b64 s[6:7], s[58:59], 18
	s_add_u32 s60, s74, s6
	s_addc_u32 s61, s75, s7
	s_and_b64 s[6:7], s[0:1], exec
	s_cselect_b32 s59, s61, s67
	s_cselect_b32 s92, s60, s66
	s_ashr_i32 s57, s56, 31
	s_lshl_b64 s[6:7], s[56:57], 18
	s_add_u32 s62, s42, s6
	s_addc_u32 s63, s43, s7
	s_and_b64 s[6:7], s[0:1], exec
	s_cselect_b32 s57, s63, s71
	s_cselect_b32 s93, s62, s70
	s_add_u32 s66, s66, 0x20080
	s_addc_u32 s67, s67, 0
	s_add_u32 s94, s70, 0x100
	s_addc_u32 s95, s71, 0
	s_mov_b32 s96, -2
	s_cmp_eq_u32 s100, 1
	s_cbranch_scc1 .Lrwp3a_prelaxed
	s_waitcnt vmcnt(0)
.Lrwp3a_pdone:
	s_branch .Lrwp3a_first

.Lrwp3a_adone:
	s_waitcnt lgkmcnt(0)
	s_barrier
	s_setprio 1
	s_waitcnt lgkmcnt(0)
	v_mfma_f32_16x16x32_bf16 v[126:129], v[154:157], v[186:189], 0
	v_mfma_f32_16x16x32_bf16 v[122:125], v[162:165], v[186:189], 0
	v_mfma_f32_16x16x32_bf16 v[114:117], v[154:157], v[194:197], 0
	v_mfma_f32_16x16x32_bf16 v[106:109], v[162:165], v[194:197], 0
	v_mfma_f32_16x16x32_bf16 v[98:101], v[154:157], v[202:205], 0
	v_mfma_f32_16x16x32_bf16 v[90:93], v[162:165], v[202:205], 0
	v_mfma_f32_16x16x32_bf16 v[82:85], v[154:157], v[210:213], 0
	v_mfma_f32_16x16x32_bf16 v[74:77], v[162:165], v[210:213], 0
	v_mfma_f32_16x16x32_bf16 v[126:129], v[158:161], v[190:193], v[126:129]
	v_mfma_f32_16x16x32_bf16 v[122:125], v[166:169], v[190:193], v[122:125]
	v_mfma_f32_16x16x32_bf16 v[114:117], v[158:161], v[198:201], v[114:117]
	v_mfma_f32_16x16x32_bf16 v[106:109], v[166:169], v[198:201], v[106:109]
	v_mfma_f32_16x16x32_bf16 v[98:101], v[158:161], v[206:209], v[98:101]
	v_mfma_f32_16x16x32_bf16 v[90:93], v[166:169], v[206:209], v[90:93]
	v_mfma_f32_16x16x32_bf16 v[82:85], v[158:161], v[214:217], v[82:85]
	v_mfma_f32_16x16x32_bf16 v[74:77], v[166:169], v[214:217], v[74:77]
	s_setprio 0
	s_setprio 1
	v_mfma_f32_16x16x32_bf16 v[118:121], v[170:173], v[186:189], 0
	v_mfma_f32_16x16x32_bf16 v[110:113], v[178:181], v[186:189], 0
	v_mfma_f32_16x16x32_bf16 v[102:105], v[170:173], v[194:197], 0
	v_mfma_f32_16x16x32_bf16 v[94:97], v[178:181], v[194:197], 0
	v_mfma_f32_16x16x32_bf16 v[86:89], v[170:173], v[202:205], 0
	v_mfma_f32_16x16x32_bf16 v[78:81], v[178:181], v[202:205], 0
	v_mfma_f32_16x16x32_bf16 v[70:73], v[170:173], v[210:213], 0
	v_mfma_f32_16x16x32_bf16 v[66:69], v[178:181], v[210:213], 0
	v_mfma_f32_16x16x32_bf16 v[118:121], v[174:177], v[190:193], v[118:121]
	v_mfma_f32_16x16x32_bf16 v[110:113], v[182:185], v[190:193], v[110:113]
	v_mfma_f32_16x16x32_bf16 v[102:105], v[174:177], v[198:201], v[102:105]
	v_mfma_f32_16x16x32_bf16 v[94:97], v[182:185], v[198:201], v[94:97]
	v_mfma_f32_16x16x32_bf16 v[86:89], v[174:177], v[206:209], v[86:89]
	v_mfma_f32_16x16x32_bf16 v[78:81], v[182:185], v[206:209], v[78:81]
	v_mfma_f32_16x16x32_bf16 v[70:73], v[174:177], v[214:217], v[70:73]
	v_mfma_f32_16x16x32_bf16 v[66:69], v[182:185], v[214:217], v[66:69]
	s_setprio 0
	s_barrier
	s_add_i32 s6, s85, s31
	v_lshl_add_u64 v[146:147], s[70:71], 0, v[132:133]
	s_mov_b32 m0, s6
	ds_read_b128 v[186:189], v152 offset:16384
	ds_read_b128 v[190:193], v152 offset:17408
	ds_read_b128 v[194:197], v152 offset:18432
	ds_read_b128 v[198:201], v152 offset:19456
	ds_read_b128 v[202:205], v152 offset:20480
	ds_read_b128 v[206:209], v152 offset:21504
	ds_read_b128 v[210:213], v152 offset:22528
	ds_read_b128 v[214:217], v152 offset:23552
	global_load_lds_dwordx4 v[146:147], off
	s_add_i32 m0, s6, 0x2000
	s_add_u32 s6, s70, 0x20000
	v_lshl_add_u64 v[218:219], s[70:71], 0, v[136:137]
	s_addc_u32 s7, s71, 0
	s_add_i32 s97, s86, s31
	global_load_lds_dwordx4 v[218:219], off
	v_lshl_add_u64 v[220:221], s[6:7], 0, v[132:133]
	s_mov_b32 m0, s97
	v_lshl_add_u64 v[222:223], s[72:73], 0, v[134:135]
	global_load_lds_dwordx4 v[220:221], off
	v_lshl_add_u64 v[220:221], s[6:7], 0, v[136:137]
	s_add_i32 m0, s97, 0x2000
	s_nop 0
	global_load_lds_dwordx4 v[220:221], off
	v_lshl_add_u64 v[220:221], s[72:73], 0, v[130:131]
	s_mov_b32 m0, s65
	s_nop 0
	global_load_lds_dwordx4 v[220:221], off
	s_mov_b32 m0, s76
	s_nop 0
	global_load_lds_dwordx4 v[222:223], off
	s_cmp_eq_u32 s100, 1
	s_cbranch_scc1 .Lrwp3a_b16
	s_waitcnt vmcnt(8)
	s_branch .Lrwp3a_bdone

.Lrwp3a_bdone:
	s_mov_b32 s100, 0
	s_waitcnt lgkmcnt(0)
	s_barrier
	s_setprio 1
	s_waitcnt lgkmcnt(0)
	v_mfma_f32_16x16x32_bf16 v[62:65], v[154:157], v[186:189], 0
	v_mfma_f32_16x16x32_bf16 v[58:61], v[162:165], v[186:189], 0
	v_mfma_f32_16x16x32_bf16 v[50:53], v[154:157], v[194:197], 0
	v_mfma_f32_16x16x32_bf16 v[42:45], v[162:165], v[194:197], 0
	v_mfma_f32_16x16x32_bf16 v[34:37], v[154:157], v[202:205], 0
	v_mfma_f32_16x16x32_bf16 v[26:29], v[162:165], v[202:205], 0
	v_mfma_f32_16x16x32_bf16 v[18:21], v[154:157], v[210:213], 0
	v_mfma_f32_16x16x32_bf16 v[10:13], v[162:165], v[210:213], 0
	v_mfma_f32_16x16x32_bf16 v[62:65], v[158:161], v[190:193], v[62:65]
	v_mfma_f32_16x16x32_bf16 v[58:61], v[166:169], v[190:193], v[58:61]
	v_mfma_f32_16x16x32_bf16 v[50:53], v[158:161], v[198:201], v[50:53]
	v_mfma_f32_16x16x32_bf16 v[42:45], v[166:169], v[198:201], v[42:45]
	v_mfma_f32_16x16x32_bf16 v[34:37], v[158:161], v[206:209], v[34:37]
	v_mfma_f32_16x16x32_bf16 v[26:29], v[166:169], v[206:209], v[26:29]
	v_mfma_f32_16x16x32_bf16 v[18:21], v[158:161], v[214:217], v[18:21]
	v_mfma_f32_16x16x32_bf16 v[10:13], v[166:169], v[214:217], v[10:13]
	s_setprio 0
	s_setprio 1
	v_mfma_f32_16x16x32_bf16 v[54:57], v[170:173], v[186:189], 0
	v_mfma_f32_16x16x32_bf16 v[46:49], v[178:181], v[186:189], 0
	v_mfma_f32_16x16x32_bf16 v[38:41], v[170:173], v[194:197], 0
	v_mfma_f32_16x16x32_bf16 v[30:33], v[178:181], v[194:197], 0
	v_mfma_f32_16x16x32_bf16 v[22:25], v[170:173], v[202:205], 0
	v_mfma_f32_16x16x32_bf16 v[14:17], v[178:181], v[202:205], 0
	v_mfma_f32_16x16x32_bf16 v[6:9], v[170:173], v[210:213], 0
	v_mfma_f32_16x16x32_bf16 v[2:5], v[178:181], v[210:213], 0
	v_mfma_f32_16x16x32_bf16 v[54:57], v[174:177], v[190:193], v[54:57]
	v_mfma_f32_16x16x32_bf16 v[46:49], v[182:185], v[190:193], v[46:49]
	v_mfma_f32_16x16x32_bf16 v[38:41], v[174:177], v[198:201], v[38:41]
	v_mfma_f32_16x16x32_bf16 v[30:33], v[182:185], v[198:201], v[30:33]
	v_mfma_f32_16x16x32_bf16 v[22:25], v[174:177], v[206:209], v[22:25]
	v_mfma_f32_16x16x32_bf16 v[14:17], v[182:185], v[206:209], v[14:17]
	v_mfma_f32_16x16x32_bf16 v[6:9], v[174:177], v[214:217], v[6:9]
	v_mfma_f32_16x16x32_bf16 v[2:5], v[182:185], v[214:217], v[2:5]
	s_setprio 0
	s_barrier
	s_add_i32 s97, 0, 0x18000
	v_add_u32_e32 v153, s97, v149
	s_add_i32 vcc_lo, 0, 0x1c000
	ds_read_b128 v[154:157], v153
	ds_read_b128 v[158:161], v153 offset:1024
	ds_read_b128 v[162:165], v153 offset:2048
	ds_read_b128 v[166:169], v153 offset:3072
	v_add_u32_e32 v153, vcc_lo, v149
	ds_read_b128 v[170:173], v153
	ds_read_b128 v[174:177], v153 offset:1024
	ds_read_b128 v[178:181], v153 offset:2048
	ds_read_b128 v[182:185], v153 offset:3072
	s_add_u32 s6, s72, 0x20000
	s_addc_u32 s7, s73, 0
	s_mov_b32 m0, s77
	v_lshl_add_u64 v[224:225], s[6:7], 0, v[130:131]
	ds_read_b128 v[186:189], v152 offset:32768
	ds_read_b128 v[190:193], v152 offset:33792
	ds_read_b128 v[194:197], v152 offset:34816
	ds_read_b128 v[198:201], v152 offset:35840
	ds_read_b128 v[202:205], v152 offset:36864
	ds_read_b128 v[206:209], v152 offset:37888
	ds_read_b128 v[210:213], v152 offset:38912
	ds_read_b128 v[214:217], v152 offset:39936
	global_load_lds_dwordx4 v[224:225], off
	v_lshl_add_u64 v[224:225], s[6:7], 0, v[134:135]
	s_mov_b32 m0, s78
	s_nop 0
	global_load_lds_dwordx4 v[224:225], off
	s_waitcnt vmcnt(8)
	s_waitcnt lgkmcnt(0)
	s_barrier
	s_setprio 1
	s_waitcnt lgkmcnt(0)
	v_mfma_f32_16x16x32_bf16 v[126:129], v[154:157], v[186:189], v[126:129]
	v_mfma_f32_16x16x32_bf16 v[122:125], v[162:165], v[186:189], v[122:125]
	v_mfma_f32_16x16x32_bf16 v[114:117], v[154:157], v[194:197], v[114:117]
	v_mfma_f32_16x16x32_bf16 v[106:109], v[162:165], v[194:197], v[106:109]
	v_mfma_f32_16x16x32_bf16 v[98:101], v[154:157], v[202:205], v[98:101]
	v_mfma_f32_16x16x32_bf16 v[90:93], v[162:165], v[202:205], v[90:93]
	v_mfma_f32_16x16x32_bf16 v[82:85], v[154:157], v[210:213], v[82:85]
	v_mfma_f32_16x16x32_bf16 v[74:77], v[162:165], v[210:213], v[74:77]
	v_mfma_f32_16x16x32_bf16 v[126:129], v[158:161], v[190:193], v[126:129]
	v_mfma_f32_16x16x32_bf16 v[122:125], v[166:169], v[190:193], v[122:125]
	v_mfma_f32_16x16x32_bf16 v[114:117], v[158:161], v[198:201], v[114:117]
	v_mfma_f32_16x16x32_bf16 v[106:109], v[166:169], v[198:201], v[106:109]
	v_mfma_f32_16x16x32_bf16 v[98:101], v[158:161], v[206:209], v[98:101]
	v_mfma_f32_16x16x32_bf16 v[90:93], v[166:169], v[206:209], v[90:93]
	v_mfma_f32_16x16x32_bf16 v[82:85], v[158:161], v[214:217], v[82:85]
	v_mfma_f32_16x16x32_bf16 v[74:77], v[166:169], v[214:217], v[74:77]
	s_setprio 0
	s_setprio 1
	v_mfma_f32_16x16x32_bf16 v[118:121], v[170:173], v[186:189], v[118:121]
	v_mfma_f32_16x16x32_bf16 v[110:113], v[178:181], v[186:189], v[110:113]
	v_mfma_f32_16x16x32_bf16 v[102:105], v[170:173], v[194:197], v[102:105]
	v_mfma_f32_16x16x32_bf16 v[94:97], v[178:181], v[194:197], v[94:97]
	v_mfma_f32_16x16x32_bf16 v[86:89], v[170:173], v[202:205], v[86:89]
	v_mfma_f32_16x16x32_bf16 v[78:81], v[178:181], v[202:205], v[78:81]
	v_mfma_f32_16x16x32_bf16 v[70:73], v[170:173], v[210:213], v[70:73]
	v_mfma_f32_16x16x32_bf16 v[66:69], v[178:181], v[210:213], v[66:69]
	v_mfma_f32_16x16x32_bf16 v[118:121], v[174:177], v[190:193], v[118:121]
	v_mfma_f32_16x16x32_bf16 v[110:113], v[182:185], v[190:193], v[110:113]
	v_mfma_f32_16x16x32_bf16 v[102:105], v[174:177], v[198:201], v[102:105]
	v_mfma_f32_16x16x32_bf16 v[94:97], v[182:185], v[198:201], v[94:97]
	v_mfma_f32_16x16x32_bf16 v[86:89], v[174:177], v[206:209], v[86:89]
	v_mfma_f32_16x16x32_bf16 v[78:81], v[182:185], v[206:209], v[78:81]
	v_mfma_f32_16x16x32_bf16 v[70:73], v[174:177], v[214:217], v[70:73]
	v_mfma_f32_16x16x32_bf16 v[66:69], v[182:185], v[214:217], v[66:69]
	s_setprio 0
	s_barrier
	s_add_i32 s6, s97, s31
	v_lshl_add_u64 v[146:147], v[146:147], 0, s[12:13]
	s_mov_b32 m0, s6
	ds_read_b128 v[186:189], v152 offset:49152
	ds_read_b128 v[190:193], v152 offset:50176
	ds_read_b128 v[194:197], v152 offset:51200
	ds_read_b128 v[198:201], v152 offset:52224
	ds_read_b128 v[202:205], v152 offset:53248
	ds_read_b128 v[206:209], v152 offset:54272
	ds_read_b128 v[210:213], v152 offset:55296
	ds_read_b128 v[214:217], v152 offset:56320
	global_load_lds_dwordx4 v[146:147], off
	s_add_i32 m0, s6, 0x2000
	s_add_u32 s6, s70, 0x20080
	v_lshl_add_u64 v[146:147], v[218:219], 0, s[12:13]
	s_addc_u32 s7, s71, 0
	s_add_i32 s70, vcc_lo, s31
	global_load_lds_dwordx4 v[146:147], off
	v_lshl_add_u64 v[146:147], s[6:7], 0, v[132:133]
	s_mov_b32 m0, s70
	s_nop 0
	global_load_lds_dwordx4 v[146:147], off
	v_lshl_add_u64 v[146:147], s[6:7], 0, v[136:137]
	s_add_i32 m0, s70, 0x2000
	s_nop 0
	global_load_lds_dwordx4 v[146:147], off
	v_lshl_add_u64 v[146:147], v[220:221], 0, s[12:13]
	s_mov_b32 m0, s82
	s_nop 0
	global_load_lds_dwordx4 v[146:147], off
	v_lshl_add_u64 v[146:147], v[222:223], 0, s[12:13]
	s_mov_b32 m0, s83
	s_nop 0
	global_load_lds_dwordx4 v[146:147], off
	s_waitcnt vmcnt(8)
	s_waitcnt lgkmcnt(0)
	s_barrier
	s_setprio 1
	s_waitcnt lgkmcnt(0)
	v_mfma_f32_16x16x32_bf16 v[62:65], v[154:157], v[186:189], v[62:65]
	v_mfma_f32_16x16x32_bf16 v[58:61], v[162:165], v[186:189], v[58:61]
	v_mfma_f32_16x16x32_bf16 v[50:53], v[154:157], v[194:197], v[50:53]
	v_mfma_f32_16x16x32_bf16 v[42:45], v[162:165], v[194:197], v[42:45]
	v_mfma_f32_16x16x32_bf16 v[34:37], v[154:157], v[202:205], v[34:37]
	v_mfma_f32_16x16x32_bf16 v[26:29], v[162:165], v[202:205], v[26:29]
	v_mfma_f32_16x16x32_bf16 v[18:21], v[154:157], v[210:213], v[18:21]
	v_mfma_f32_16x16x32_bf16 v[10:13], v[162:165], v[210:213], v[10:13]
	v_mfma_f32_16x16x32_bf16 v[62:65], v[158:161], v[190:193], v[62:65]
	v_mfma_f32_16x16x32_bf16 v[58:61], v[166:169], v[190:193], v[58:61]
	v_mfma_f32_16x16x32_bf16 v[50:53], v[158:161], v[198:201], v[50:53]
	v_mfma_f32_16x16x32_bf16 v[42:45], v[166:169], v[198:201], v[42:45]
	v_mfma_f32_16x16x32_bf16 v[34:37], v[158:161], v[206:209], v[34:37]
	v_mfma_f32_16x16x32_bf16 v[26:29], v[166:169], v[206:209], v[26:29]
	v_mfma_f32_16x16x32_bf16 v[18:21], v[158:161], v[214:217], v[18:21]
	v_mfma_f32_16x16x32_bf16 v[10:13], v[166:169], v[214:217], v[10:13]
	s_setprio 0
	s_setprio 1
	v_mfma_f32_16x16x32_bf16 v[54:57], v[170:173], v[186:189], v[54:57]
	v_mfma_f32_16x16x32_bf16 v[46:49], v[178:181], v[186:189], v[46:49]
	v_mfma_f32_16x16x32_bf16 v[38:41], v[170:173], v[194:197], v[38:41]
	v_mfma_f32_16x16x32_bf16 v[30:33], v[178:181], v[194:197], v[30:33]
	v_mfma_f32_16x16x32_bf16 v[22:25], v[170:173], v[202:205], v[22:25]
	v_mfma_f32_16x16x32_bf16 v[14:17], v[178:181], v[202:205], v[14:17]
	v_mfma_f32_16x16x32_bf16 v[6:9], v[170:173], v[210:213], v[6:9]
	v_mfma_f32_16x16x32_bf16 v[2:5], v[178:181], v[210:213], v[2:5]
	v_mfma_f32_16x16x32_bf16 v[54:57], v[174:177], v[190:193], v[54:57]
	v_mfma_f32_16x16x32_bf16 v[46:49], v[182:185], v[190:193], v[46:49]
	v_mfma_f32_16x16x32_bf16 v[38:41], v[174:177], v[198:201], v[38:41]
	v_mfma_f32_16x16x32_bf16 v[30:33], v[182:185], v[198:201], v[30:33]
	v_mfma_f32_16x16x32_bf16 v[22:25], v[174:177], v[206:209], v[22:25]
	v_mfma_f32_16x16x32_bf16 v[14:17], v[182:185], v[206:209], v[14:17]
	v_mfma_f32_16x16x32_bf16 v[6:9], v[174:177], v[214:217], v[6:9]
	v_mfma_f32_16x16x32_bf16 v[2:5], v[182:185], v[214:217], v[2:5]
	s_setprio 0
	s_barrier
	s_add_i32 s96, s96, 2
	s_add_u32 s66, s66, 0x100
	s_addc_u32 s67, s67, 0
	s_add_u32 s94, s94, 0x100
	s_addc_u32 s95, s95, 0
	s_cmp_gt_u32 s96, 5
	s_cbranch_scc0 .LBB0_560
	s_branch .Lrwp3a_exit

.LBB0_583:
	s_ashr_i32 s63, s62, 31
	s_lshl_b64 s[6:7], s[62:63], 18
	s_add_u32 s64, s4, s6
	s_addc_u32 s65, s5, s7
	s_and_b64 s[6:7], s[0:1], exec
	s_cselect_b32 s63, s65, s73
	s_cselect_b32 s90, s64, s72
	s_ashr_i32 s61, s60, 31
	s_lshl_b64 s[6:7], s[60:61], 18
	s_add_u32 s66, s40, s6
	s_addc_u32 s67, s41, s7
	s_and_b64 s[6:7], s[0:1], exec
	s_cselect_b32 s61, s67, s75
	s_cselect_b32 s91, s66, s74
	s_add_u32 s72, s72, 0x20080
	s_addc_u32 s73, s73, 0
	s_add_u32 s92, s74, 0x100
	s_addc_u32 s93, s75, 0
	s_mov_b32 s94, -2
	s_cmp_eq_u32 s100, 1
	s_cbranch_scc1 .Lrwp3b_prelaxed
	s_waitcnt vmcnt(0)

.Lrwp3b_adone:
	s_waitcnt lgkmcnt(0)
	s_barrier
	s_setprio 1
	s_waitcnt lgkmcnt(0)
	v_mfma_f32_16x16x32_bf16 v[126:129], v[154:157], v[186:189], 0
	v_mfma_f32_16x16x32_bf16 v[122:125], v[162:165], v[186:189], 0
	v_mfma_f32_16x16x32_bf16 v[110:113], v[154:157], v[194:197], 0
	v_mfma_f32_16x16x32_bf16 v[106:109], v[162:165], v[194:197], 0
	v_mfma_f32_16x16x32_bf16 v[94:97], v[154:157], v[202:205], 0
	v_mfma_f32_16x16x32_bf16 v[90:93], v[162:165], v[202:205], 0
	v_mfma_f32_16x16x32_bf16 v[78:81], v[154:157], v[210:213], 0
	v_mfma_f32_16x16x32_bf16 v[74:77], v[162:165], v[210:213], 0
	v_mfma_f32_16x16x32_bf16 v[126:129], v[158:161], v[190:193], v[126:129]
	v_mfma_f32_16x16x32_bf16 v[122:125], v[166:169], v[190:193], v[122:125]
	v_mfma_f32_16x16x32_bf16 v[110:113], v[158:161], v[198:201], v[110:113]
	v_mfma_f32_16x16x32_bf16 v[106:109], v[166:169], v[198:201], v[106:109]
	v_mfma_f32_16x16x32_bf16 v[94:97], v[158:161], v[206:209], v[94:97]
	v_mfma_f32_16x16x32_bf16 v[90:93], v[166:169], v[206:209], v[90:93]
	v_mfma_f32_16x16x32_bf16 v[78:81], v[158:161], v[214:217], v[78:81]
	v_mfma_f32_16x16x32_bf16 v[74:77], v[166:169], v[214:217], v[74:77]
	s_setprio 0
	s_setprio 1
	v_mfma_f32_16x16x32_bf16 v[118:121], v[170:173], v[186:189], 0
	v_mfma_f32_16x16x32_bf16 v[114:117], v[178:181], v[186:189], 0
	v_mfma_f32_16x16x32_bf16 v[102:105], v[170:173], v[194:197], 0
	v_mfma_f32_16x16x32_bf16 v[98:101], v[178:181], v[194:197], 0
	v_mfma_f32_16x16x32_bf16 v[86:89], v[170:173], v[202:205], 0
	v_mfma_f32_16x16x32_bf16 v[82:85], v[178:181], v[202:205], 0
	v_mfma_f32_16x16x32_bf16 v[70:73], v[170:173], v[210:213], 0
	v_mfma_f32_16x16x32_bf16 v[66:69], v[178:181], v[210:213], 0
	v_mfma_f32_16x16x32_bf16 v[118:121], v[174:177], v[190:193], v[118:121]
	v_mfma_f32_16x16x32_bf16 v[114:117], v[182:185], v[190:193], v[114:117]
	v_mfma_f32_16x16x32_bf16 v[102:105], v[174:177], v[198:201], v[102:105]
	v_mfma_f32_16x16x32_bf16 v[98:101], v[182:185], v[198:201], v[98:101]
	v_mfma_f32_16x16x32_bf16 v[86:89], v[174:177], v[206:209], v[86:89]
	v_mfma_f32_16x16x32_bf16 v[82:85], v[182:185], v[206:209], v[82:85]
	v_mfma_f32_16x16x32_bf16 v[70:73], v[174:177], v[214:217], v[70:73]
	v_mfma_f32_16x16x32_bf16 v[66:69], v[182:185], v[214:217], v[66:69]
	s_setprio 0
	s_barrier
	s_add_i32 s6, s87, s31
	v_lshl_add_u64 v[146:147], s[74:75], 0, v[132:133]
	s_mov_b32 m0, s6
	ds_read_b128 v[186:189], v152 offset:16384
	ds_read_b128 v[190:193], v152 offset:17408
	ds_read_b128 v[194:197], v152 offset:18432
	ds_read_b128 v[198:201], v152 offset:19456
	ds_read_b128 v[202:205], v152 offset:20480
	ds_read_b128 v[206:209], v152 offset:21504
	ds_read_b128 v[210:213], v152 offset:22528
	ds_read_b128 v[214:217], v152 offset:23552
	global_load_lds_dwordx4 v[146:147], off
	s_add_i32 m0, s6, 0x2000
	s_add_u32 s6, s74, 0x20000
	v_lshl_add_u64 v[218:219], s[74:75], 0, v[136:137]
	s_addc_u32 s7, s75, 0
	s_add_i32 s95, s88, s31
	global_load_lds_dwordx4 v[218:219], off
	v_lshl_add_u64 v[220:221], s[6:7], 0, v[132:133]
	s_mov_b32 m0, s95
	v_lshl_add_u64 v[222:223], s[76:77], 0, v[134:135]
	global_load_lds_dwordx4 v[220:221], off
	v_lshl_add_u64 v[220:221], s[6:7], 0, v[136:137]
	s_add_i32 m0, s95, 0x2000
	s_nop 0
	global_load_lds_dwordx4 v[220:221], off
	v_lshl_add_u64 v[220:221], s[76:77], 0, v[130:131]
	s_mov_b32 m0, s71
	s_nop 0
	global_load_lds_dwordx4 v[220:221], off
	s_mov_b32 m0, s78
	s_nop 0
	global_load_lds_dwordx4 v[222:223], off
	s_cmp_eq_u32 s100, 1
	s_cbranch_scc1 .Lrwp3b_b8
	s_waitcnt vmcnt(8)
	s_branch .Lrwp3b_bdone

.Lrwp3b_bdone:
	s_mov_b32 s100, 0
	s_waitcnt lgkmcnt(0)
	s_barrier
	s_setprio 1
	s_waitcnt lgkmcnt(0)
	v_mfma_f32_16x16x32_bf16 v[62:65], v[154:157], v[186:189], 0
	v_mfma_f32_16x16x32_bf16 v[58:61], v[162:165], v[186:189], 0
	v_mfma_f32_16x16x32_bf16 v[46:49], v[154:157], v[194:197], 0
	v_mfma_f32_16x16x32_bf16 v[42:45], v[162:165], v[194:197], 0
	v_mfma_f32_16x16x32_bf16 v[30:33], v[154:157], v[202:205], 0
	v_mfma_f32_16x16x32_bf16 v[26:29], v[162:165], v[202:205], 0
	v_mfma_f32_16x16x32_bf16 v[14:17], v[154:157], v[210:213], 0
	v_mfma_f32_16x16x32_bf16 v[10:13], v[162:165], v[210:213], 0
	v_mfma_f32_16x16x32_bf16 v[62:65], v[158:161], v[190:193], v[62:65]
	v_mfma_f32_16x16x32_bf16 v[58:61], v[166:169], v[190:193], v[58:61]
	v_mfma_f32_16x16x32_bf16 v[46:49], v[158:161], v[198:201], v[46:49]
	v_mfma_f32_16x16x32_bf16 v[42:45], v[166:169], v[198:201], v[42:45]
	v_mfma_f32_16x16x32_bf16 v[30:33], v[158:161], v[206:209], v[30:33]
	v_mfma_f32_16x16x32_bf16 v[26:29], v[166:169], v[206:209], v[26:29]
	v_mfma_f32_16x16x32_bf16 v[14:17], v[158:161], v[214:217], v[14:17]
	v_mfma_f32_16x16x32_bf16 v[10:13], v[166:169], v[214:217], v[10:13]
	s_setprio 0
	s_setprio 1
	v_mfma_f32_16x16x32_bf16 v[54:57], v[170:173], v[186:189], 0
	v_mfma_f32_16x16x32_bf16 v[50:53], v[178:181], v[186:189], 0
	v_mfma_f32_16x16x32_bf16 v[38:41], v[170:173], v[194:197], 0
	v_mfma_f32_16x16x32_bf16 v[34:37], v[178:181], v[194:197], 0
	v_mfma_f32_16x16x32_bf16 v[22:25], v[170:173], v[202:205], 0
	v_mfma_f32_16x16x32_bf16 v[18:21], v[178:181], v[202:205], 0
	v_mfma_f32_16x16x32_bf16 v[6:9], v[170:173], v[210:213], 0
	v_mfma_f32_16x16x32_bf16 v[2:5], v[178:181], v[210:213], 0
	v_mfma_f32_16x16x32_bf16 v[54:57], v[174:177], v[190:193], v[54:57]
	v_mfma_f32_16x16x32_bf16 v[50:53], v[182:185], v[190:193], v[50:53]
	v_mfma_f32_16x16x32_bf16 v[38:41], v[174:177], v[198:201], v[38:41]
	v_mfma_f32_16x16x32_bf16 v[34:37], v[182:185], v[198:201], v[34:37]
	v_mfma_f32_16x16x32_bf16 v[22:25], v[174:177], v[206:209], v[22:25]
	v_mfma_f32_16x16x32_bf16 v[18:21], v[182:185], v[206:209], v[18:21]
	v_mfma_f32_16x16x32_bf16 v[6:9], v[174:177], v[214:217], v[6:9]
	v_mfma_f32_16x16x32_bf16 v[2:5], v[182:185], v[214:217], v[2:5]
	s_setprio 0
	s_barrier
	s_add_i32 s95, 0, 0x18000
	v_add_u32_e32 v153, s95, v149
	s_add_i32 s96, 0, 0x1c000
	ds_read_b128 v[154:157], v153
	ds_read_b128 v[158:161], v153 offset:1024
	ds_read_b128 v[162:165], v153 offset:2048
	ds_read_b128 v[166:169], v153 offset:3072
	v_add_u32_e32 v153, s96, v149
	ds_read_b128 v[170:173], v153
	ds_read_b128 v[174:177], v153 offset:1024
	ds_read_b128 v[178:181], v153 offset:2048
	ds_read_b128 v[182:185], v153 offset:3072
	s_add_u32 s6, s76, 0x20000
	s_addc_u32 s7, s77, 0
	s_mov_b32 m0, s79
	v_lshl_add_u64 v[224:225], s[6:7], 0, v[130:131]
	ds_read_b128 v[186:189], v152 offset:32768
	ds_read_b128 v[190:193], v152 offset:33792
	ds_read_b128 v[194:197], v152 offset:34816
	ds_read_b128 v[198:201], v152 offset:35840
	ds_read_b128 v[202:205], v152 offset:36864
	ds_read_b128 v[206:209], v152 offset:37888
	ds_read_b128 v[210:213], v152 offset:38912
	ds_read_b128 v[214:217], v152 offset:39936
	global_load_lds_dwordx4 v[224:225], off
	v_lshl_add_u64 v[224:225], s[6:7], 0, v[134:135]
	s_mov_b32 m0, s80
	s_nop 0
	global_load_lds_dwordx4 v[224:225], off
	s_waitcnt vmcnt(8)
	s_waitcnt lgkmcnt(0)
	s_barrier
	s_setprio 1
	s_waitcnt lgkmcnt(0)
	v_mfma_f32_16x16x32_bf16 v[126:129], v[154:157], v[186:189], v[126:129]
	v_mfma_f32_16x16x32_bf16 v[122:125], v[162:165], v[186:189], v[122:125]
	v_mfma_f32_16x16x32_bf16 v[110:113], v[154:157], v[194:197], v[110:113]
	v_mfma_f32_16x16x32_bf16 v[106:109], v[162:165], v[194:197], v[106:109]
	v_mfma_f32_16x16x32_bf16 v[94:97], v[154:157], v[202:205], v[94:97]
	v_mfma_f32_16x16x32_bf16 v[90:93], v[162:165], v[202:205], v[90:93]
	v_mfma_f32_16x16x32_bf16 v[78:81], v[154:157], v[210:213], v[78:81]
	v_mfma_f32_16x16x32_bf16 v[74:77], v[162:165], v[210:213], v[74:77]
	v_mfma_f32_16x16x32_bf16 v[126:129], v[158:161], v[190:193], v[126:129]
	v_mfma_f32_16x16x32_bf16 v[122:125], v[166:169], v[190:193], v[122:125]
	v_mfma_f32_16x16x32_bf16 v[110:113], v[158:161], v[198:201], v[110:113]
	v_mfma_f32_16x16x32_bf16 v[106:109], v[166:169], v[198:201], v[106:109]
	v_mfma_f32_16x16x32_bf16 v[94:97], v[158:161], v[206:209], v[94:97]
	v_mfma_f32_16x16x32_bf16 v[90:93], v[166:169], v[206:209], v[90:93]
	v_mfma_f32_16x16x32_bf16 v[78:81], v[158:161], v[214:217], v[78:81]
	v_mfma_f32_16x16x32_bf16 v[74:77], v[166:169], v[214:217], v[74:77]
	s_setprio 0
	s_setprio 1
	v_mfma_f32_16x16x32_bf16 v[118:121], v[170:173], v[186:189], v[118:121]
	v_mfma_f32_16x16x32_bf16 v[114:117], v[178:181], v[186:189], v[114:117]
	v_mfma_f32_16x16x32_bf16 v[102:105], v[170:173], v[194:197], v[102:105]
	v_mfma_f32_16x16x32_bf16 v[98:101], v[178:181], v[194:197], v[98:101]
	v_mfma_f32_16x16x32_bf16 v[86:89], v[170:173], v[202:205], v[86:89]
	v_mfma_f32_16x16x32_bf16 v[82:85], v[178:181], v[202:205], v[82:85]
	v_mfma_f32_16x16x32_bf16 v[70:73], v[170:173], v[210:213], v[70:73]
	v_mfma_f32_16x16x32_bf16 v[66:69], v[178:181], v[210:213], v[66:69]
	v_mfma_f32_16x16x32_bf16 v[118:121], v[174:177], v[190:193], v[118:121]
	v_mfma_f32_16x16x32_bf16 v[114:117], v[182:185], v[190:193], v[114:117]
	v_mfma_f32_16x16x32_bf16 v[102:105], v[174:177], v[198:201], v[102:105]
	v_mfma_f32_16x16x32_bf16 v[98:101], v[182:185], v[198:201], v[98:101]
	v_mfma_f32_16x16x32_bf16 v[86:89], v[174:177], v[206:209], v[86:89]
	v_mfma_f32_16x16x32_bf16 v[82:85], v[182:185], v[206:209], v[82:85]
	v_mfma_f32_16x16x32_bf16 v[70:73], v[174:177], v[214:217], v[70:73]
	v_mfma_f32_16x16x32_bf16 v[66:69], v[182:185], v[214:217], v[66:69]
	s_setprio 0
	s_barrier
	s_add_i32 s6, s95, s31
	v_lshl_add_u64 v[146:147], v[146:147], 0, s[20:21]
	s_mov_b32 m0, s6
	ds_read_b128 v[186:189], v152 offset:49152
	ds_read_b128 v[190:193], v152 offset:50176
	ds_read_b128 v[194:197], v152 offset:51200
	ds_read_b128 v[198:201], v152 offset:52224
	ds_read_b128 v[202:205], v152 offset:53248
	ds_read_b128 v[206:209], v152 offset:54272
	ds_read_b128 v[210:213], v152 offset:55296
	ds_read_b128 v[214:217], v152 offset:56320
	global_load_lds_dwordx4 v[146:147], off
	s_add_i32 m0, s6, 0x2000
	s_add_u32 s6, s74, 0x20080
	v_lshl_add_u64 v[146:147], v[218:219], 0, s[20:21]
	s_addc_u32 s7, s75, 0
	s_add_i32 s74, s96, s31
	global_load_lds_dwordx4 v[146:147], off
	v_lshl_add_u64 v[146:147], s[6:7], 0, v[132:133]
	s_mov_b32 m0, s74
	s_nop 0
	global_load_lds_dwordx4 v[146:147], off
	v_lshl_add_u64 v[146:147], s[6:7], 0, v[136:137]
	s_add_i32 m0, s74, 0x2000
	s_nop 0
	global_load_lds_dwordx4 v[146:147], off
	v_lshl_add_u64 v[146:147], v[220:221], 0, s[20:21]
	s_mov_b32 m0, s84
	s_nop 0
	global_load_lds_dwordx4 v[146:147], off
	v_lshl_add_u64 v[146:147], v[222:223], 0, s[20:21]
	s_mov_b32 m0, s85
	s_nop 0
	global_load_lds_dwordx4 v[146:147], off
	s_waitcnt vmcnt(8)
	s_waitcnt lgkmcnt(0)
	s_barrier
	s_setprio 1
	s_waitcnt lgkmcnt(0)
	v_mfma_f32_16x16x32_bf16 v[62:65], v[154:157], v[186:189], v[62:65]
	v_mfma_f32_16x16x32_bf16 v[58:61], v[162:165], v[186:189], v[58:61]
	v_mfma_f32_16x16x32_bf16 v[46:49], v[154:157], v[194:197], v[46:49]
	v_mfma_f32_16x16x32_bf16 v[42:45], v[162:165], v[194:197], v[42:45]
	v_mfma_f32_16x16x32_bf16 v[30:33], v[154:157], v[202:205], v[30:33]
	v_mfma_f32_16x16x32_bf16 v[26:29], v[162:165], v[202:205], v[26:29]
	v_mfma_f32_16x16x32_bf16 v[14:17], v[154:157], v[210:213], v[14:17]
	v_mfma_f32_16x16x32_bf16 v[10:13], v[162:165], v[210:213], v[10:13]
	v_mfma_f32_16x16x32_bf16 v[62:65], v[158:161], v[190:193], v[62:65]
	v_mfma_f32_16x16x32_bf16 v[58:61], v[166:169], v[190:193], v[58:61]
	v_mfma_f32_16x16x32_bf16 v[46:49], v[158:161], v[198:201], v[46:49]
	v_mfma_f32_16x16x32_bf16 v[42:45], v[166:169], v[198:201], v[42:45]
	v_mfma_f32_16x16x32_bf16 v[30:33], v[158:161], v[206:209], v[30:33]
	v_mfma_f32_16x16x32_bf16 v[26:29], v[166:169], v[206:209], v[26:29]
	v_mfma_f32_16x16x32_bf16 v[14:17], v[158:161], v[214:217], v[14:17]
	v_mfma_f32_16x16x32_bf16 v[10:13], v[166:169], v[214:217], v[10:13]
	s_setprio 0
	s_setprio 1
	v_mfma_f32_16x16x32_bf16 v[54:57], v[170:173], v[186:189], v[54:57]
	v_mfma_f32_16x16x32_bf16 v[50:53], v[178:181], v[186:189], v[50:53]
	v_mfma_f32_16x16x32_bf16 v[38:41], v[170:173], v[194:197], v[38:41]
	v_mfma_f32_16x16x32_bf16 v[34:37], v[178:181], v[194:197], v[34:37]
	v_mfma_f32_16x16x32_bf16 v[22:25], v[170:173], v[202:205], v[22:25]
	v_mfma_f32_16x16x32_bf16 v[18:21], v[178:181], v[202:205], v[18:21]
	v_mfma_f32_16x16x32_bf16 v[6:9], v[170:173], v[210:213], v[6:9]
	v_mfma_f32_16x16x32_bf16 v[2:5], v[178:181], v[210:213], v[2:5]
	v_mfma_f32_16x16x32_bf16 v[54:57], v[174:177], v[190:193], v[54:57]
	v_mfma_f32_16x16x32_bf16 v[50:53], v[182:185], v[190:193], v[50:53]
	v_mfma_f32_16x16x32_bf16 v[38:41], v[174:177], v[198:201], v[38:41]
	v_mfma_f32_16x16x32_bf16 v[34:37], v[182:185], v[198:201], v[34:37]
	v_mfma_f32_16x16x32_bf16 v[22:25], v[174:177], v[206:209], v[22:25]
	v_mfma_f32_16x16x32_bf16 v[18:21], v[182:185], v[206:209], v[18:21]
	v_mfma_f32_16x16x32_bf16 v[6:9], v[174:177], v[214:217], v[6:9]
	v_mfma_f32_16x16x32_bf16 v[2:5], v[182:185], v[214:217], v[2:5]
	s_setprio 0
	s_barrier
	s_add_i32 s94, s94, 2
	s_add_u32 s72, s72, 0x100
	s_addc_u32 s73, s73, 0
	s_add_u32 s92, s92, 0x100
	s_addc_u32 s93, s93, 0
	s_cmp_gt_u32 s94, 5
	s_cbranch_scc0 .LBB0_584
	s_branch .Lrwp3b_exit

.LBB0_779:
	s_ashr_i32 s43, s42, 31
	s_lshl_b64 s[6:7], s[42:43], 19
	s_add_u32 s44, s18, s6
	s_addc_u32 s45, s19, s7
	s_and_b64 s[6:7], s[0:1], exec
	s_cselect_b32 s43, s45, s49
	s_cselect_b32 s78, s44, s48
	s_ashr_i32 s39, s38, 31
	s_lshl_b64 s[6:7], s[38:39], 19
	s_add_u32 s46, s34, s6
	s_addc_u32 s47, s35, s7
	s_and_b64 s[6:7], s[0:1], exec
	s_cselect_b32 s39, s47, s51
	s_cselect_b32 s79, s46, s50
	s_add_u32 s48, s48, 0x40080
	s_addc_u32 s49, s49, 0
	s_add_u32 s80, s50, 0x100
	s_addc_u32 s81, s51, 0
	s_mov_b32 s82, -2
	s_branch .Lrwp6_first

.Lrwp6_adone:
	s_waitcnt lgkmcnt(0)
	s_barrier
	s_setprio 1
	s_waitcnt lgkmcnt(0)
	v_mfma_f32_16x16x32_bf16 v[126:129], v[156:159], v[188:191], 0
	v_mfma_f32_16x16x32_bf16 v[122:125], v[164:167], v[188:191], 0
	v_mfma_f32_16x16x32_bf16 v[110:113], v[156:159], v[196:199], 0
	v_mfma_f32_16x16x32_bf16 v[106:109], v[164:167], v[196:199], 0
	v_mfma_f32_16x16x32_bf16 v[94:97], v[156:159], v[204:207], 0
	v_mfma_f32_16x16x32_bf16 v[90:93], v[164:167], v[204:207], 0
	v_mfma_f32_16x16x32_bf16 v[78:81], v[156:159], v[212:215], 0
	v_mfma_f32_16x16x32_bf16 v[74:77], v[164:167], v[212:215], 0
	v_mfma_f32_16x16x32_bf16 v[126:129], v[160:163], v[192:195], v[126:129]
	v_mfma_f32_16x16x32_bf16 v[122:125], v[168:171], v[192:195], v[122:125]
	v_mfma_f32_16x16x32_bf16 v[110:113], v[160:163], v[200:203], v[110:113]
	v_mfma_f32_16x16x32_bf16 v[106:109], v[168:171], v[200:203], v[106:109]
	v_mfma_f32_16x16x32_bf16 v[94:97], v[160:163], v[208:211], v[94:97]
	v_mfma_f32_16x16x32_bf16 v[90:93], v[168:171], v[208:211], v[90:93]
	v_mfma_f32_16x16x32_bf16 v[78:81], v[160:163], v[216:219], v[78:81]
	v_mfma_f32_16x16x32_bf16 v[74:77], v[168:171], v[216:219], v[74:77]
	s_setprio 0
	s_setprio 1
	v_mfma_f32_16x16x32_bf16 v[118:121], v[172:175], v[188:191], 0
	v_mfma_f32_16x16x32_bf16 v[114:117], v[180:183], v[188:191], 0
	v_mfma_f32_16x16x32_bf16 v[102:105], v[172:175], v[196:199], 0
	v_mfma_f32_16x16x32_bf16 v[98:101], v[180:183], v[196:199], 0
	v_mfma_f32_16x16x32_bf16 v[86:89], v[172:175], v[204:207], 0
	v_mfma_f32_16x16x32_bf16 v[82:85], v[180:183], v[204:207], 0
	v_mfma_f32_16x16x32_bf16 v[70:73], v[172:175], v[212:215], 0
	v_mfma_f32_16x16x32_bf16 v[66:69], v[180:183], v[212:215], 0
	v_mfma_f32_16x16x32_bf16 v[118:121], v[176:179], v[192:195], v[118:121]
	v_mfma_f32_16x16x32_bf16 v[114:117], v[184:187], v[192:195], v[114:117]
	v_mfma_f32_16x16x32_bf16 v[102:105], v[176:179], v[200:203], v[102:105]
	v_mfma_f32_16x16x32_bf16 v[98:101], v[184:187], v[200:203], v[98:101]
	v_mfma_f32_16x16x32_bf16 v[86:89], v[176:179], v[208:211], v[86:89]
	v_mfma_f32_16x16x32_bf16 v[82:85], v[184:187], v[208:211], v[82:85]
	v_mfma_f32_16x16x32_bf16 v[70:73], v[176:179], v[216:219], v[70:73]
	v_mfma_f32_16x16x32_bf16 v[66:69], v[184:187], v[216:219], v[66:69]
	s_setprio 0
	s_barrier
	s_add_i32 s6, s63, s31
	v_lshl_add_u64 v[148:149], s[50:51], 0, v[132:133]
	s_mov_b32 m0, s6
	ds_read_b128 v[188:191], v154 offset:16384
	ds_read_b128 v[192:195], v154 offset:17408
	ds_read_b128 v[196:199], v154 offset:18432
	ds_read_b128 v[200:203], v154 offset:19456
	ds_read_b128 v[204:207], v154 offset:20480
	ds_read_b128 v[208:211], v154 offset:21504
	ds_read_b128 v[212:215], v154 offset:22528
	ds_read_b128 v[216:219], v154 offset:23552
	global_load_lds_dwordx4 v[148:149], off
	s_add_i32 m0, s6, 0x2000
	s_add_u32 s6, s50, 0x40000
	v_lshl_add_u64 v[220:221], s[50:51], 0, v[136:137]
	s_addc_u32 s7, s51, 0
	s_add_i32 s83, s64, s31
	global_load_lds_dwordx4 v[220:221], off
	v_lshl_add_u64 v[222:223], s[6:7], 0, v[132:133]
	s_mov_b32 m0, s83
	v_lshl_add_u64 v[224:225], s[52:53], 0, v[134:135]
	global_load_lds_dwordx4 v[222:223], off
	v_lshl_add_u64 v[222:223], s[6:7], 0, v[136:137]
	s_add_i32 m0, s83, 0x2000
	s_nop 0
	global_load_lds_dwordx4 v[222:223], off
	v_lshl_add_u64 v[222:223], s[52:53], 0, v[130:131]
	s_mov_b32 m0, s54
	s_nop 0
	global_load_lds_dwordx4 v[222:223], off
	s_mov_b32 m0, s55
	s_nop 0
	global_load_lds_dwordx4 v[224:225], off
	s_cmp_eq_u32 s98, 1
	s_cbranch_scc1 .Lrwp6_b16
	s_waitcnt vmcnt(8)
	s_branch .Lrwp6_bdone

.Lrwp6_bdone:
	s_mov_b32 s98, 0
	s_waitcnt lgkmcnt(0)
	s_barrier
	s_setprio 1
	s_waitcnt lgkmcnt(0)
	v_mfma_f32_16x16x32_bf16 v[62:65], v[156:159], v[188:191], 0
	v_mfma_f32_16x16x32_bf16 v[58:61], v[164:167], v[188:191], 0
	v_mfma_f32_16x16x32_bf16 v[46:49], v[156:159], v[196:199], 0
	v_mfma_f32_16x16x32_bf16 v[42:45], v[164:167], v[196:199], 0
	v_mfma_f32_16x16x32_bf16 v[30:33], v[156:159], v[204:207], 0
	v_mfma_f32_16x16x32_bf16 v[26:29], v[164:167], v[204:207], 0
	v_mfma_f32_16x16x32_bf16 v[14:17], v[156:159], v[212:215], 0
	v_mfma_f32_16x16x32_bf16 v[10:13], v[164:167], v[212:215], 0
	v_mfma_f32_16x16x32_bf16 v[62:65], v[160:163], v[192:195], v[62:65]
	v_mfma_f32_16x16x32_bf16 v[58:61], v[168:171], v[192:195], v[58:61]
	v_mfma_f32_16x16x32_bf16 v[46:49], v[160:163], v[200:203], v[46:49]
	v_mfma_f32_16x16x32_bf16 v[42:45], v[168:171], v[200:203], v[42:45]
	v_mfma_f32_16x16x32_bf16 v[30:33], v[160:163], v[208:211], v[30:33]
	v_mfma_f32_16x16x32_bf16 v[26:29], v[168:171], v[208:211], v[26:29]
	v_mfma_f32_16x16x32_bf16 v[14:17], v[160:163], v[216:219], v[14:17]
	v_mfma_f32_16x16x32_bf16 v[10:13], v[168:171], v[216:219], v[10:13]
	s_setprio 0
	s_setprio 1
	v_mfma_f32_16x16x32_bf16 v[54:57], v[172:175], v[188:191], 0
	v_mfma_f32_16x16x32_bf16 v[50:53], v[180:183], v[188:191], 0
	v_mfma_f32_16x16x32_bf16 v[38:41], v[172:175], v[196:199], 0
	v_mfma_f32_16x16x32_bf16 v[34:37], v[180:183], v[196:199], 0
	v_mfma_f32_16x16x32_bf16 v[22:25], v[172:175], v[204:207], 0
	v_mfma_f32_16x16x32_bf16 v[18:21], v[180:183], v[204:207], 0
	v_mfma_f32_16x16x32_bf16 v[6:9], v[172:175], v[212:215], 0
	v_mfma_f32_16x16x32_bf16 v[2:5], v[180:183], v[212:215], 0
	v_mfma_f32_16x16x32_bf16 v[54:57], v[176:179], v[192:195], v[54:57]
	v_mfma_f32_16x16x32_bf16 v[50:53], v[184:187], v[192:195], v[50:53]
	v_mfma_f32_16x16x32_bf16 v[38:41], v[176:179], v[200:203], v[38:41]
	v_mfma_f32_16x16x32_bf16 v[34:37], v[184:187], v[200:203], v[34:37]
	v_mfma_f32_16x16x32_bf16 v[22:25], v[176:179], v[208:211], v[22:25]
	v_mfma_f32_16x16x32_bf16 v[18:21], v[184:187], v[208:211], v[18:21]
	v_mfma_f32_16x16x32_bf16 v[6:9], v[176:179], v[216:219], v[6:9]
	v_mfma_f32_16x16x32_bf16 v[2:5], v[184:187], v[216:219], v[2:5]
	s_setprio 0
	s_barrier
	s_add_i32 s83, 0, 0x18000
	v_add_u32_e32 v138, s83, v151
	s_add_i32 s84, 0, 0x1c000
	ds_read_b128 v[156:159], v138
	ds_read_b128 v[160:163], v138 offset:1024
	ds_read_b128 v[164:167], v138 offset:2048
	ds_read_b128 v[168:171], v138 offset:3072
	v_add_u32_e32 v138, s84, v151
	ds_read_b128 v[172:175], v138
	ds_read_b128 v[176:179], v138 offset:1024
	ds_read_b128 v[180:183], v138 offset:2048
	ds_read_b128 v[184:187], v138 offset:3072
	s_add_u32 s6, s52, 0x40000
	s_addc_u32 s7, s53, 0
	s_mov_b32 m0, s56
	v_lshl_add_u64 v[226:227], s[6:7], 0, v[130:131]
	ds_read_b128 v[188:191], v154 offset:32768
	ds_read_b128 v[192:195], v154 offset:33792
	ds_read_b128 v[196:199], v154 offset:34816
	ds_read_b128 v[200:203], v154 offset:35840
	ds_read_b128 v[204:207], v154 offset:36864
	ds_read_b128 v[208:211], v154 offset:37888
	ds_read_b128 v[212:215], v154 offset:38912
	ds_read_b128 v[216:219], v154 offset:39936
	global_load_lds_dwordx4 v[226:227], off
	v_lshl_add_u64 v[226:227], s[6:7], 0, v[134:135]
	s_mov_b32 m0, s57
	s_nop 0
	global_load_lds_dwordx4 v[226:227], off
	s_waitcnt vmcnt(8)
	s_waitcnt lgkmcnt(0)
	s_barrier
	s_setprio 1
	s_waitcnt lgkmcnt(0)
	v_mfma_f32_16x16x32_bf16 v[126:129], v[156:159], v[188:191], v[126:129]
	v_mfma_f32_16x16x32_bf16 v[122:125], v[164:167], v[188:191], v[122:125]
	v_mfma_f32_16x16x32_bf16 v[110:113], v[156:159], v[196:199], v[110:113]
	v_mfma_f32_16x16x32_bf16 v[106:109], v[164:167], v[196:199], v[106:109]
	v_mfma_f32_16x16x32_bf16 v[94:97], v[156:159], v[204:207], v[94:97]
	v_mfma_f32_16x16x32_bf16 v[90:93], v[164:167], v[204:207], v[90:93]
	v_mfma_f32_16x16x32_bf16 v[78:81], v[156:159], v[212:215], v[78:81]
	v_mfma_f32_16x16x32_bf16 v[74:77], v[164:167], v[212:215], v[74:77]
	v_mfma_f32_16x16x32_bf16 v[126:129], v[160:163], v[192:195], v[126:129]
	v_mfma_f32_16x16x32_bf16 v[122:125], v[168:171], v[192:195], v[122:125]
	v_mfma_f32_16x16x32_bf16 v[110:113], v[160:163], v[200:203], v[110:113]
	v_mfma_f32_16x16x32_bf16 v[106:109], v[168:171], v[200:203], v[106:109]
	v_mfma_f32_16x16x32_bf16 v[94:97], v[160:163], v[208:211], v[94:97]
	v_mfma_f32_16x16x32_bf16 v[90:93], v[168:171], v[208:211], v[90:93]
	v_mfma_f32_16x16x32_bf16 v[78:81], v[160:163], v[216:219], v[78:81]
	v_mfma_f32_16x16x32_bf16 v[74:77], v[168:171], v[216:219], v[74:77]
	s_setprio 0
	s_setprio 1
	v_mfma_f32_16x16x32_bf16 v[118:121], v[172:175], v[188:191], v[118:121]
	v_mfma_f32_16x16x32_bf16 v[114:117], v[180:183], v[188:191], v[114:117]
	v_mfma_f32_16x16x32_bf16 v[102:105], v[172:175], v[196:199], v[102:105]
	v_mfma_f32_16x16x32_bf16 v[98:101], v[180:183], v[196:199], v[98:101]
	v_mfma_f32_16x16x32_bf16 v[86:89], v[172:175], v[204:207], v[86:89]
	v_mfma_f32_16x16x32_bf16 v[82:85], v[180:183], v[204:207], v[82:85]
	v_mfma_f32_16x16x32_bf16 v[70:73], v[172:175], v[212:215], v[70:73]
	v_mfma_f32_16x16x32_bf16 v[66:69], v[180:183], v[212:215], v[66:69]
	v_mfma_f32_16x16x32_bf16 v[118:121], v[176:179], v[192:195], v[118:121]
	v_mfma_f32_16x16x32_bf16 v[114:117], v[184:187], v[192:195], v[114:117]
	v_mfma_f32_16x16x32_bf16 v[102:105], v[176:179], v[200:203], v[102:105]
	v_mfma_f32_16x16x32_bf16 v[98:101], v[184:187], v[200:203], v[98:101]
	v_mfma_f32_16x16x32_bf16 v[86:89], v[176:179], v[208:211], v[86:89]
	v_mfma_f32_16x16x32_bf16 v[82:85], v[184:187], v[208:211], v[82:85]
	v_mfma_f32_16x16x32_bf16 v[70:73], v[176:179], v[216:219], v[70:73]
	v_mfma_f32_16x16x32_bf16 v[66:69], v[184:187], v[216:219], v[66:69]
	s_setprio 0
	s_barrier
	s_add_i32 s6, s83, s31
	v_lshl_add_u64 v[148:149], v[148:149], 0, s[16:17]
	s_mov_b32 m0, s6
	ds_read_b128 v[188:191], v154 offset:49152
	ds_read_b128 v[192:195], v154 offset:50176
	ds_read_b128 v[196:199], v154 offset:51200
	ds_read_b128 v[200:203], v154 offset:52224
	ds_read_b128 v[204:207], v154 offset:53248
	ds_read_b128 v[208:211], v154 offset:54272
	ds_read_b128 v[212:215], v154 offset:55296
	ds_read_b128 v[216:219], v154 offset:56320
	global_load_lds_dwordx4 v[148:149], off
	s_add_i32 m0, s6, 0x2000
	s_add_u32 s6, s50, 0x40080
	v_lshl_add_u64 v[148:149], v[220:221], 0, s[16:17]
	s_addc_u32 s7, s51, 0
	s_add_i32 s50, s84, s31
	global_load_lds_dwordx4 v[148:149], off
	v_lshl_add_u64 v[148:149], s[6:7], 0, v[132:133]
	s_mov_b32 m0, s50
	s_nop 0
	global_load_lds_dwordx4 v[148:149], off
	v_lshl_add_u64 v[148:149], s[6:7], 0, v[136:137]
	s_add_i32 m0, s50, 0x2000
	s_nop 0
	global_load_lds_dwordx4 v[148:149], off
	v_lshl_add_u64 v[148:149], v[222:223], 0, s[16:17]
	s_mov_b32 m0, s60
	s_nop 0
	global_load_lds_dwordx4 v[148:149], off
	v_lshl_add_u64 v[148:149], v[224:225], 0, s[16:17]
	s_mov_b32 m0, s61
	s_nop 0
	global_load_lds_dwordx4 v[148:149], off
	s_waitcnt vmcnt(8)
	s_waitcnt lgkmcnt(0)
	s_barrier
	s_setprio 1
	s_waitcnt lgkmcnt(0)
	v_mfma_f32_16x16x32_bf16 v[62:65], v[156:159], v[188:191], v[62:65]
	v_mfma_f32_16x16x32_bf16 v[58:61], v[164:167], v[188:191], v[58:61]
	v_mfma_f32_16x16x32_bf16 v[46:49], v[156:159], v[196:199], v[46:49]
	v_mfma_f32_16x16x32_bf16 v[42:45], v[164:167], v[196:199], v[42:45]
	v_mfma_f32_16x16x32_bf16 v[30:33], v[156:159], v[204:207], v[30:33]
	v_mfma_f32_16x16x32_bf16 v[26:29], v[164:167], v[204:207], v[26:29]
	v_mfma_f32_16x16x32_bf16 v[14:17], v[156:159], v[212:215], v[14:17]
	v_mfma_f32_16x16x32_bf16 v[10:13], v[164:167], v[212:215], v[10:13]
	v_mfma_f32_16x16x32_bf16 v[62:65], v[160:163], v[192:195], v[62:65]
	v_mfma_f32_16x16x32_bf16 v[58:61], v[168:171], v[192:195], v[58:61]
	v_mfma_f32_16x16x32_bf16 v[46:49], v[160:163], v[200:203], v[46:49]
	v_mfma_f32_16x16x32_bf16 v[42:45], v[168:171], v[200:203], v[42:45]
	v_mfma_f32_16x16x32_bf16 v[30:33], v[160:163], v[208:211], v[30:33]
	v_mfma_f32_16x16x32_bf16 v[26:29], v[168:171], v[208:211], v[26:29]
	v_mfma_f32_16x16x32_bf16 v[14:17], v[160:163], v[216:219], v[14:17]
	v_mfma_f32_16x16x32_bf16 v[10:13], v[168:171], v[216:219], v[10:13]
	s_setprio 0
	s_setprio 1
	v_mfma_f32_16x16x32_bf16 v[54:57], v[172:175], v[188:191], v[54:57]
	v_mfma_f32_16x16x32_bf16 v[50:53], v[180:183], v[188:191], v[50:53]
	v_mfma_f32_16x16x32_bf16 v[38:41], v[172:175], v[196:199], v[38:41]
	v_mfma_f32_16x16x32_bf16 v[34:37], v[180:183], v[196:199], v[34:37]
	v_mfma_f32_16x16x32_bf16 v[22:25], v[172:175], v[204:207], v[22:25]
	v_mfma_f32_16x16x32_bf16 v[18:21], v[180:183], v[204:207], v[18:21]
	v_mfma_f32_16x16x32_bf16 v[6:9], v[172:175], v[212:215], v[6:9]
	v_mfma_f32_16x16x32_bf16 v[2:5], v[180:183], v[212:215], v[2:5]
	v_mfma_f32_16x16x32_bf16 v[54:57], v[176:179], v[192:195], v[54:57]
	v_mfma_f32_16x16x32_bf16 v[50:53], v[184:187], v[192:195], v[50:53]
	v_mfma_f32_16x16x32_bf16 v[38:41], v[176:179], v[200:203], v[38:41]
	v_mfma_f32_16x16x32_bf16 v[34:37], v[184:187], v[200:203], v[34:37]
	v_mfma_f32_16x16x32_bf16 v[22:25], v[176:179], v[208:211], v[22:25]
	v_mfma_f32_16x16x32_bf16 v[18:21], v[184:187], v[208:211], v[18:21]
	v_mfma_f32_16x16x32_bf16 v[6:9], v[176:179], v[216:219], v[6:9]
	v_mfma_f32_16x16x32_bf16 v[2:5], v[184:187], v[216:219], v[2:5]
	s_setprio 0
	s_barrier
	s_add_i32 s82, s82, 2
	s_add_u32 s48, s48, 0x100
	s_addc_u32 s49, s49, 0
	s_add_u32 s80, s80, 0x100
	s_addc_u32 s81, s81, 0
	s_cmp_gt_u32 s82, 13
	s_cbranch_scc0 .LBB0_780
	s_branch .Lrwp6_exit
